# all ten GEMM K-loops: LDS-DMA loads use scalar base + 32-bit lane offset (no 64-bit VALU address add per load; bases kept in SGPR pairs, s98-s101 as temporaries); on top of non-scaled MFMA
# speedup vs baseline: 1.0082x; 1.0002x over previous
.LBB0_250:
	s_waitcnt lgkmcnt(0)
	s_barrier
	s_setprio 1
	s_waitcnt lgkmcnt(0)
	v_mfma_f32_16x16x128_f8f6f4 v[126:129], v[26:33], v[58:65], v[126:129]
	v_mfma_f32_16x16x128_f8f6f4 v[122:125], v[18:25], v[58:65], v[122:125]
	v_mfma_f32_16x16x128_f8f6f4 v[110:113], v[26:33], v[50:57], v[110:113]
	v_mfma_f32_16x16x128_f8f6f4 v[106:109], v[18:25], v[50:57], v[106:109]
	v_mfma_f32_16x16x128_f8f6f4 v[94:97], v[26:33], v[42:49], v[94:97]
	v_mfma_f32_16x16x128_f8f6f4 v[90:93], v[18:25], v[42:49], v[90:93]
	v_mfma_f32_16x16x128_f8f6f4 v[78:81], v[26:33], v[34:41], v[78:81]
	v_mfma_f32_16x16x128_f8f6f4 v[74:77], v[18:25], v[34:41], v[74:77]
	s_setprio 0
	s_setprio 1
	v_mfma_f32_16x16x128_f8f6f4 v[118:121], v[10:17], v[58:65], v[118:121]
	v_mfma_f32_16x16x128_f8f6f4 v[114:117], v[2:9], v[58:65], v[114:117]
	v_mfma_f32_16x16x128_f8f6f4 v[102:105], v[10:17], v[50:57], v[102:105]
	v_mfma_f32_16x16x128_f8f6f4 v[98:101], v[2:9], v[50:57], v[98:101]
	v_mfma_f32_16x16x128_f8f6f4 v[86:89], v[10:17], v[42:49], v[86:89]
	v_mfma_f32_16x16x128_f8f6f4 v[82:85], v[2:9], v[42:49], v[82:85]
	v_mfma_f32_16x16x128_f8f6f4 v[70:73], v[10:17], v[34:41], v[70:73]
	v_mfma_f32_16x16x128_f8f6f4 v[66:69], v[2:9], v[34:41], v[66:69]
	s_setprio 0
	s_barrier
	v_add_u32_e32 v14, s53, v205
	v_add_u32_e32 v30, s58, v205
	ds_read_b128 v[2:5], v14
	ds_read_b128 v[6:9], v14 offset:1024
	ds_read_b128 v[10:13], v14 offset:2048
	ds_read_b128 v[14:17], v14 offset:3072
	ds_read_b128 v[18:21], v30
	ds_read_b128 v[22:25], v30 offset:1024
	ds_read_b128 v[26:29], v30 offset:2048
	ds_read_b128 v[30:33], v30 offset:3072
	s_add_u32 s100, s36, 0x530000
	s_addc_u32 s101, s37, 0
	s_mov_b32 m0, s51
	ds_read_b128 v[34:37], v234 offset:32768
	ds_read_b128 v[38:41], v234 offset:33792
	ds_read_b128 v[42:45], v234 offset:34816
	ds_read_b128 v[46:49], v234 offset:35840
	ds_read_b128 v[50:53], v234 offset:36864
	ds_read_b128 v[54:57], v234 offset:37888
	ds_read_b128 v[58:61], v234 offset:38912
	ds_read_b128 v[62:65], v234 offset:39936
	global_load_lds_dwordx4 v194, s[100:101]
	s_mov_b32 m0, s52
	s_nop 0
	global_load_lds_dwordx4 v198, s[100:101]
	s_waitcnt vmcnt(8)
	s_waitcnt lgkmcnt(0)
	s_barrier
	s_setprio 1
	s_waitcnt lgkmcnt(0)
	v_mfma_f32_16x16x128_f8f6f4 v[190:193], v[2:9], v[34:41], v[190:193]
	v_mfma_f32_16x16x128_f8f6f4 v[186:189], v[10:17], v[34:41], v[186:189]
	v_mfma_f32_16x16x128_f8f6f4 v[174:177], v[2:9], v[42:49], v[174:177]
	v_mfma_f32_16x16x128_f8f6f4 v[170:173], v[10:17], v[42:49], v[170:173]
	v_mfma_f32_16x16x128_f8f6f4 v[158:161], v[2:9], v[50:57], v[158:161]
	v_mfma_f32_16x16x128_f8f6f4 v[154:157], v[10:17], v[50:57], v[154:157]
	v_mfma_f32_16x16x128_f8f6f4 v[142:145], v[2:9], v[58:65], v[142:145]
	v_mfma_f32_16x16x128_f8f6f4 v[138:141], v[10:17], v[58:65], v[138:141]
	s_setprio 0
	s_setprio 1
	v_mfma_f32_16x16x128_f8f6f4 v[182:185], v[18:25], v[34:41], v[182:185]
	v_mfma_f32_16x16x128_f8f6f4 v[178:181], v[26:33], v[34:41], v[178:181]
	v_mfma_f32_16x16x128_f8f6f4 v[166:169], v[18:25], v[42:49], v[166:169]
	v_mfma_f32_16x16x128_f8f6f4 v[162:165], v[26:33], v[42:49], v[162:165]
	v_mfma_f32_16x16x128_f8f6f4 v[150:153], v[18:25], v[50:57], v[150:153]
	v_mfma_f32_16x16x128_f8f6f4 v[146:149], v[26:33], v[50:57], v[146:149]
	v_mfma_f32_16x16x128_f8f6f4 v[134:137], v[18:25], v[58:65], v[134:137]
	v_mfma_f32_16x16x128_f8f6f4 v[130:133], v[26:33], v[58:65], v[130:133]
	s_setprio 0
	s_barrier
	s_mov_b32 m0, s54
	ds_read_b128 v[34:37], v234 offset:49152
	ds_read_b128 v[38:41], v234 offset:50176
	ds_read_b128 v[42:45], v234 offset:51200
	ds_read_b128 v[46:49], v234 offset:52224
	ds_read_b128 v[50:53], v234 offset:53248
	ds_read_b128 v[54:57], v234 offset:54272
	ds_read_b128 v[58:61], v234 offset:55296
	ds_read_b128 v[62:65], v234 offset:56320
	s_add_u32 s98, s34, 0x80
	s_addc_u32 s99, s35, 0
	global_load_lds_dwordx4 v196, s[98:99]
	s_mov_b32 m0, s55
	s_nop 0
	global_load_lds_dwordx4 v200, s[98:99]
	s_mov_b32 m0, s59
	s_nop 0
	s_add_u32 s100, s82, 0x80
	s_addc_u32 s101, s83, 0
	global_load_lds_dwordx4 v196, s[100:101]
	s_mov_b32 m0, s60
	s_nop 0
	global_load_lds_dwordx4 v200, s[100:101]
	s_mov_b32 m0, s56
	s_nop 0
	s_add_u32 s98, s36, 0x80
	s_addc_u32 s99, s37, 0
	global_load_lds_dwordx4 v194, s[98:99]
	s_mov_b32 m0, s57
	s_nop 0
	global_load_lds_dwordx4 v198, s[98:99]
	s_waitcnt vmcnt(8)
	s_waitcnt lgkmcnt(0)
	s_barrier
	s_setprio 1
	s_waitcnt lgkmcnt(0)
	v_mfma_f32_16x16x128_f8f6f4 v[126:129], v[2:9], v[34:41], v[126:129]
	v_mfma_f32_16x16x128_f8f6f4 v[122:125], v[10:17], v[34:41], v[122:125]
	v_mfma_f32_16x16x128_f8f6f4 v[110:113], v[2:9], v[42:49], v[110:113]
	v_mfma_f32_16x16x128_f8f6f4 v[106:109], v[10:17], v[42:49], v[106:109]
	v_mfma_f32_16x16x128_f8f6f4 v[94:97], v[2:9], v[50:57], v[94:97]
	v_mfma_f32_16x16x128_f8f6f4 v[90:93], v[10:17], v[50:57], v[90:93]
	v_mfma_f32_16x16x128_f8f6f4 v[78:81], v[2:9], v[58:65], v[78:81]
	v_mfma_f32_16x16x128_f8f6f4 v[74:77], v[10:17], v[58:65], v[74:77]
	s_setprio 0
	s_setprio 1
	v_mfma_f32_16x16x128_f8f6f4 v[118:121], v[18:25], v[34:41], v[118:121]
	v_mfma_f32_16x16x128_f8f6f4 v[114:117], v[26:33], v[34:41], v[114:117]
	v_mfma_f32_16x16x128_f8f6f4 v[102:105], v[18:25], v[42:49], v[102:105]
	v_mfma_f32_16x16x128_f8f6f4 v[98:101], v[26:33], v[42:49], v[98:101]
	v_mfma_f32_16x16x128_f8f6f4 v[86:89], v[18:25], v[50:57], v[86:89]
	v_mfma_f32_16x16x128_f8f6f4 v[82:85], v[26:33], v[50:57], v[82:85]
	v_mfma_f32_16x16x128_f8f6f4 v[70:73], v[18:25], v[58:65], v[70:73]
	v_mfma_f32_16x16x128_f8f6f4 v[66:69], v[26:33], v[58:65], v[66:69]
	s_setprio 0
	s_barrier
	s_add_i32 s80, s80, 2
	s_add_u32 s30, s30, 0x100
	s_addc_u32 s31, s31, 0
	s_cmp_gt_u32 s80, 13
	s_cbranch_scc1 .LBB0_258
.LBB0_251:
	s_cmp_eq_u32 s30, 0
	s_cselect_b64 s[34:35], -1, 0
	s_and_b64 s[34:35], s[0:1], s[34:35]
	v_cndmask_b32_e64 v2, 0, 1, s[34:35]
	s_nop 0
	v_readfirstlane_b32 s34, v2
	s_and_b32 s34, s34, 1
	ds_read_b128 v[26:29], v232
	ds_read_b128 v[30:33], v232 offset:1024
	ds_read_b128 v[18:21], v232 offset:2048
	ds_read_b128 v[22:25], v232 offset:3072
	ds_read_b128 v[10:13], v233
	ds_read_b128 v[14:17], v233 offset:1024
	ds_read_b128 v[2:5], v233 offset:2048
	ds_read_b128 v[6:9], v233 offset:3072
	s_add_u32 s98, s6, s30
	s_addc_u32 s99, s7, s31
	s_add_i32 m0, s49, 0xc000
	ds_read_b128 v[58:61], v234
	ds_read_b128 v[62:65], v234 offset:1024
	ds_read_b128 v[50:53], v234 offset:2048
	ds_read_b128 v[54:57], v234 offset:3072
	ds_read_b128 v[42:45], v234 offset:4096
	ds_read_b128 v[46:49], v234 offset:5120
	ds_read_b128 v[34:37], v234 offset:6144
	ds_read_b128 v[38:41], v234 offset:7168
	global_load_lds_dwordx4 v212, s[98:99]
	s_add_i32 m0, s49, 0xe000
	s_cmp_lg_u32 s34, 0
	global_load_lds_dwordx4 v210, s[98:99]
	s_cselect_b64 s[38:39], -1, 0
	s_cmp_eq_u32 s34, 0
	s_cbranch_scc1 .LBB0_256
	s_waitcnt vmcnt(16)
	s_cbranch_execnz .LBB0_254

.LBB0_254:
	s_add_u32 s34, s6, s30
	s_addc_u32 s35, s7, s31
	s_add_u32 s34, s34, 0x100
	s_addc_u32 s35, s35, 0
	s_add_u32 s81, s78, s30
	s_addc_u32 s82, s79, s31
	s_waitcnt lgkmcnt(0)
	s_cmpk_eq_i32 s30, 0x700
	s_cselect_b32 s37, s27, s35
	s_cselect_b32 s36, s26, s34
	s_cselect_b32 s35, s5, s82
	s_cselect_b32 s34, s25, s81
	s_barrier
	s_setprio 1
	s_waitcnt lgkmcnt(0)
	v_mfma_f32_16x16x128_f8f6f4 v[190:193], v[26:33], v[58:65], v[190:193]
	v_mfma_f32_16x16x128_f8f6f4 v[186:189], v[18:25], v[58:65], v[186:189]
	v_mfma_f32_16x16x128_f8f6f4 v[174:177], v[26:33], v[50:57], v[174:177]
	v_mfma_f32_16x16x128_f8f6f4 v[170:173], v[18:25], v[50:57], v[170:173]
	v_mfma_f32_16x16x128_f8f6f4 v[158:161], v[26:33], v[42:49], v[158:161]
	v_mfma_f32_16x16x128_f8f6f4 v[154:157], v[18:25], v[42:49], v[154:157]
	v_mfma_f32_16x16x128_f8f6f4 v[142:145], v[26:33], v[34:41], v[142:145]
	v_mfma_f32_16x16x128_f8f6f4 v[138:141], v[18:25], v[34:41], v[138:141]
	s_setprio 0
	s_setprio 1
	v_mfma_f32_16x16x128_f8f6f4 v[182:185], v[10:17], v[58:65], v[182:185]
	v_mfma_f32_16x16x128_f8f6f4 v[178:181], v[2:9], v[58:65], v[178:181]
	v_mfma_f32_16x16x128_f8f6f4 v[166:169], v[10:17], v[50:57], v[166:169]
	v_mfma_f32_16x16x128_f8f6f4 v[162:165], v[2:9], v[50:57], v[162:165]
	v_mfma_f32_16x16x128_f8f6f4 v[150:153], v[10:17], v[42:49], v[150:153]
	v_mfma_f32_16x16x128_f8f6f4 v[146:149], v[2:9], v[42:49], v[146:149]
	v_mfma_f32_16x16x128_f8f6f4 v[134:137], v[10:17], v[34:41], v[134:137]
	v_mfma_f32_16x16x128_f8f6f4 v[130:133], v[2:9], v[34:41], v[130:133]
	s_setprio 0
	s_barrier
	s_mov_b32 m0, s45
	s_add_u32 s82, s34, 0x40000
	ds_read_b128 v[58:61], v234 offset:16384
	ds_read_b128 v[62:65], v234 offset:17408
	ds_read_b128 v[50:53], v234 offset:18432
	ds_read_b128 v[54:57], v234 offset:19456
	ds_read_b128 v[42:45], v234 offset:20480
	ds_read_b128 v[46:49], v234 offset:21504
	ds_read_b128 v[34:37], v234 offset:22528
	ds_read_b128 v[38:41], v234 offset:23552
	global_load_lds_dwordx4 v196, s[34:35]
	s_mov_b32 m0, s46
	s_addc_u32 s83, s35, 0
	global_load_lds_dwordx4 v200, s[34:35]
	s_mov_b32 m0, s47
	s_nop 0
	global_load_lds_dwordx4 v196, s[82:83]
	s_mov_b32 m0, s48
	s_andn2_b64 vcc, exec, s[38:39]
	global_load_lds_dwordx4 v200, s[82:83]
	s_mov_b32 m0, s49
	s_nop 0
	global_load_lds_dwordx4 v194, s[36:37]
	s_mov_b32 m0, s50
	s_nop 0
	global_load_lds_dwordx4 v198, s[36:37]
	s_cbranch_vccnz .LBB0_257
	s_waitcnt vmcnt(16)
	s_cbranch_execnz .LBB0_250
	s_branch .LBB0_249

.LBB0_885:
	s_waitcnt lgkmcnt(0)
	s_barrier
	s_setprio 1
	s_waitcnt lgkmcnt(0)
	v_mfma_f32_16x16x128_f8f6f4 v[126:129], v[26:33], v[58:65], v[126:129]
	v_mfma_f32_16x16x128_f8f6f4 v[122:125], v[18:25], v[58:65], v[122:125]
	v_mfma_f32_16x16x128_f8f6f4 v[110:113], v[26:33], v[50:57], v[110:113]
	v_mfma_f32_16x16x128_f8f6f4 v[106:109], v[18:25], v[50:57], v[106:109]
	v_mfma_f32_16x16x128_f8f6f4 v[94:97], v[26:33], v[42:49], v[94:97]
	v_mfma_f32_16x16x128_f8f6f4 v[90:93], v[18:25], v[42:49], v[90:93]
	v_mfma_f32_16x16x128_f8f6f4 v[78:81], v[26:33], v[34:41], v[78:81]
	v_mfma_f32_16x16x128_f8f6f4 v[74:77], v[18:25], v[34:41], v[74:77]
	s_setprio 0
	s_setprio 1
	v_mfma_f32_16x16x128_f8f6f4 v[118:121], v[10:17], v[58:65], v[118:121]
	v_mfma_f32_16x16x128_f8f6f4 v[114:117], v[2:9], v[58:65], v[114:117]
	v_mfma_f32_16x16x128_f8f6f4 v[102:105], v[10:17], v[50:57], v[102:105]
	v_mfma_f32_16x16x128_f8f6f4 v[98:101], v[2:9], v[50:57], v[98:101]
	v_mfma_f32_16x16x128_f8f6f4 v[86:89], v[10:17], v[42:49], v[86:89]
	v_mfma_f32_16x16x128_f8f6f4 v[82:85], v[2:9], v[42:49], v[82:85]
	v_mfma_f32_16x16x128_f8f6f4 v[70:73], v[10:17], v[34:41], v[70:73]
	v_mfma_f32_16x16x128_f8f6f4 v[66:69], v[2:9], v[34:41], v[66:69]
	s_setprio 0
	s_barrier
	v_add_u32_e32 v14, s48, v222
	v_add_u32_e32 v30, s53, v222
	ds_read_b128 v[2:5], v14
	ds_read_b128 v[6:9], v14 offset:1024
	ds_read_b128 v[10:13], v14 offset:2048
	ds_read_b128 v[14:17], v14 offset:3072
	ds_read_b128 v[18:21], v30
	ds_read_b128 v[22:25], v30 offset:1024
	ds_read_b128 v[26:29], v30 offset:2048
	ds_read_b128 v[30:33], v30 offset:3072
	s_add_u32 s100, s28, 0x530000
	s_addc_u32 s101, s29, 0
	s_mov_b32 m0, s42
	ds_read_b128 v[34:37], v226 offset:32768
	ds_read_b128 v[38:41], v226 offset:33792
	ds_read_b128 v[42:45], v226 offset:34816
	ds_read_b128 v[46:49], v226 offset:35840
	ds_read_b128 v[50:53], v226 offset:36864
	ds_read_b128 v[54:57], v226 offset:37888
	ds_read_b128 v[58:61], v226 offset:38912
	ds_read_b128 v[62:65], v226 offset:39936
	global_load_lds_dwordx4 v194, s[100:101]
	s_mov_b32 m0, s43
	s_nop 0
	global_load_lds_dwordx4 v198, s[100:101]
	s_waitcnt vmcnt(8)
	s_waitcnt lgkmcnt(0)
	s_barrier
	s_setprio 1
	s_waitcnt lgkmcnt(0)
	v_mfma_f32_16x16x128_f8f6f4 v[190:193], v[2:9], v[34:41], v[190:193]
	v_mfma_f32_16x16x128_f8f6f4 v[186:189], v[10:17], v[34:41], v[186:189]
	v_mfma_f32_16x16x128_f8f6f4 v[174:177], v[2:9], v[42:49], v[174:177]
	v_mfma_f32_16x16x128_f8f6f4 v[170:173], v[10:17], v[42:49], v[170:173]
	v_mfma_f32_16x16x128_f8f6f4 v[158:161], v[2:9], v[50:57], v[158:161]
	v_mfma_f32_16x16x128_f8f6f4 v[154:157], v[10:17], v[50:57], v[154:157]
	v_mfma_f32_16x16x128_f8f6f4 v[142:145], v[2:9], v[58:65], v[142:145]
	v_mfma_f32_16x16x128_f8f6f4 v[138:141], v[10:17], v[58:65], v[138:141]
	s_setprio 0
	s_setprio 1
	v_mfma_f32_16x16x128_f8f6f4 v[182:185], v[18:25], v[34:41], v[182:185]
	v_mfma_f32_16x16x128_f8f6f4 v[178:181], v[26:33], v[34:41], v[178:181]
	v_mfma_f32_16x16x128_f8f6f4 v[166:169], v[18:25], v[42:49], v[166:169]
	v_mfma_f32_16x16x128_f8f6f4 v[162:165], v[26:33], v[42:49], v[162:165]
	v_mfma_f32_16x16x128_f8f6f4 v[150:153], v[18:25], v[50:57], v[150:153]
	v_mfma_f32_16x16x128_f8f6f4 v[146:149], v[26:33], v[50:57], v[146:149]
	v_mfma_f32_16x16x128_f8f6f4 v[134:137], v[18:25], v[58:65], v[134:137]
	v_mfma_f32_16x16x128_f8f6f4 v[130:133], v[26:33], v[58:65], v[130:133]
	s_setprio 0
	s_barrier
	s_mov_b32 m0, s49
	ds_read_b128 v[34:37], v226 offset:49152
	ds_read_b128 v[38:41], v226 offset:50176
	ds_read_b128 v[42:45], v226 offset:51200
	ds_read_b128 v[46:49], v226 offset:52224
	ds_read_b128 v[50:53], v226 offset:53248
	ds_read_b128 v[54:57], v226 offset:54272
	ds_read_b128 v[58:61], v226 offset:55296
	ds_read_b128 v[62:65], v226 offset:56320
	s_add_u32 s98, s26, 0x80
	s_addc_u32 s99, s27, 0
	global_load_lds_dwordx4 v196, s[98:99]
	s_mov_b32 m0, s50
	s_nop 0
	global_load_lds_dwordx4 v200, s[98:99]
	s_mov_b32 m0, s54
	s_nop 0
	s_add_u32 s100, s72, 0x80
	s_addc_u32 s101, s73, 0
	global_load_lds_dwordx4 v196, s[100:101]
	s_mov_b32 m0, s55
	s_nop 0
	global_load_lds_dwordx4 v200, s[100:101]
	s_mov_b32 m0, s51
	s_nop 0
	s_add_u32 s98, s28, 0x100
	s_addc_u32 s99, s29, 0
	global_load_lds_dwordx4 v194, s[98:99]
	s_mov_b32 m0, s52
	s_nop 0
	global_load_lds_dwordx4 v198, s[98:99]
	s_waitcnt vmcnt(8)
	s_waitcnt lgkmcnt(0)
	s_barrier
	s_setprio 1
	s_waitcnt lgkmcnt(0)
	v_mfma_f32_16x16x128_f8f6f4 v[126:129], v[2:9], v[34:41], v[126:129]
	v_mfma_f32_16x16x128_f8f6f4 v[122:125], v[10:17], v[34:41], v[122:125]
	v_mfma_f32_16x16x128_f8f6f4 v[110:113], v[2:9], v[42:49], v[110:113]
	v_mfma_f32_16x16x128_f8f6f4 v[106:109], v[10:17], v[42:49], v[106:109]
	v_mfma_f32_16x16x128_f8f6f4 v[94:97], v[2:9], v[50:57], v[94:97]
	v_mfma_f32_16x16x128_f8f6f4 v[90:93], v[10:17], v[50:57], v[90:93]
	v_mfma_f32_16x16x128_f8f6f4 v[78:81], v[2:9], v[58:65], v[78:81]
	v_mfma_f32_16x16x128_f8f6f4 v[74:77], v[10:17], v[58:65], v[74:77]
	s_setprio 0
	s_setprio 1
	v_mfma_f32_16x16x128_f8f6f4 v[118:121], v[18:25], v[34:41], v[118:121]
	v_mfma_f32_16x16x128_f8f6f4 v[114:117], v[26:33], v[34:41], v[114:117]
	v_mfma_f32_16x16x128_f8f6f4 v[102:105], v[18:25], v[42:49], v[102:105]
	v_mfma_f32_16x16x128_f8f6f4 v[98:101], v[26:33], v[42:49], v[98:101]
	v_mfma_f32_16x16x128_f8f6f4 v[86:89], v[18:25], v[50:57], v[86:89]
	v_mfma_f32_16x16x128_f8f6f4 v[82:85], v[26:33], v[50:57], v[82:85]
	v_mfma_f32_16x16x128_f8f6f4 v[70:73], v[18:25], v[58:65], v[70:73]
	v_mfma_f32_16x16x128_f8f6f4 v[66:69], v[26:33], v[58:65], v[66:69]
	s_setprio 0
	s_barrier
	s_add_i32 s70, s70, 2
	s_add_u32 s6, s6, 0x200
	s_addc_u32 s7, s7, 0
	s_add_u32 s68, s68, 0x100
	s_addc_u32 s69, s69, 0
	s_cmp_gt_u32 s70, 13
	s_cbranch_scc1 .LBB0_893
.LBB0_886:
	s_cmp_eq_u32 s6, 0
	s_cselect_b64 s[26:27], -1, 0
	s_and_b64 s[26:27], s[0:1], s[26:27]
	v_cndmask_b32_e64 v2, 0, 1, s[26:27]
	s_nop 0
	v_readfirstlane_b32 s26, v2
	s_and_b32 s26, s26, 1
	ds_read_b128 v[26:29], v224
	ds_read_b128 v[30:33], v224 offset:1024
	ds_read_b128 v[18:21], v224 offset:2048
	ds_read_b128 v[22:25], v224 offset:3072
	ds_read_b128 v[10:13], v225
	ds_read_b128 v[14:17], v225 offset:1024
	ds_read_b128 v[2:5], v225 offset:2048
	ds_read_b128 v[6:9], v225 offset:3072
	s_add_u32 s98, s4, s6
	s_addc_u32 s99, s5, s7
	s_add_i32 m0, s40, 0xc000
	ds_read_b128 v[58:61], v226
	ds_read_b128 v[62:65], v226 offset:1024
	ds_read_b128 v[50:53], v226 offset:2048
	ds_read_b128 v[54:57], v226 offset:3072
	ds_read_b128 v[42:45], v226 offset:4096
	ds_read_b128 v[46:49], v226 offset:5120
	ds_read_b128 v[34:37], v226 offset:6144
	ds_read_b128 v[38:41], v226 offset:7168
	global_load_lds_dwordx4 v204, s[98:99]
	s_add_i32 m0, s40, 0xe000
	s_cmp_lg_u32 s26, 0
	global_load_lds_dwordx4 v202, s[98:99]
	s_cselect_b64 s[30:31], -1, 0
	s_cmp_eq_u32 s26, 0
	s_cbranch_scc1 .LBB0_891
	s_waitcnt vmcnt(24)
	s_cbranch_execnz .LBB0_889

.LBB0_889:
	s_add_u32 s26, s4, s6
	s_addc_u32 s27, s5, s7
	s_add_u32 s26, s26, 0x200
	s_addc_u32 s27, s27, 0
	s_waitcnt lgkmcnt(0)
	s_cmpk_eq_i32 s6, 0xe00
	s_cselect_b32 s29, s23, s27
	s_cselect_b32 s28, s22, s26
	s_cselect_b32 s27, s66, s69
	s_cselect_b32 s26, s67, s68
	s_barrier
	s_setprio 1
	s_waitcnt lgkmcnt(0)
	v_mfma_f32_16x16x128_f8f6f4 v[190:193], v[26:33], v[58:65], v[190:193]
	v_mfma_f32_16x16x128_f8f6f4 v[186:189], v[18:25], v[58:65], v[186:189]
	v_mfma_f32_16x16x128_f8f6f4 v[174:177], v[26:33], v[50:57], v[174:177]
	v_mfma_f32_16x16x128_f8f6f4 v[170:173], v[18:25], v[50:57], v[170:173]
	v_mfma_f32_16x16x128_f8f6f4 v[158:161], v[26:33], v[42:49], v[158:161]
	v_mfma_f32_16x16x128_f8f6f4 v[154:157], v[18:25], v[42:49], v[154:157]
	v_mfma_f32_16x16x128_f8f6f4 v[142:145], v[26:33], v[34:41], v[142:145]
	v_mfma_f32_16x16x128_f8f6f4 v[138:141], v[18:25], v[34:41], v[138:141]
	s_setprio 0
	s_setprio 1
	v_mfma_f32_16x16x128_f8f6f4 v[182:185], v[10:17], v[58:65], v[182:185]
	v_mfma_f32_16x16x128_f8f6f4 v[178:181], v[2:9], v[58:65], v[178:181]
	v_mfma_f32_16x16x128_f8f6f4 v[166:169], v[10:17], v[50:57], v[166:169]
	v_mfma_f32_16x16x128_f8f6f4 v[162:165], v[2:9], v[50:57], v[162:165]
	v_mfma_f32_16x16x128_f8f6f4 v[150:153], v[10:17], v[42:49], v[150:153]
	v_mfma_f32_16x16x128_f8f6f4 v[146:149], v[2:9], v[42:49], v[146:149]
	v_mfma_f32_16x16x128_f8f6f4 v[134:137], v[10:17], v[34:41], v[134:137]
	v_mfma_f32_16x16x128_f8f6f4 v[130:133], v[2:9], v[34:41], v[130:133]
	s_setprio 0
	s_barrier
	s_mov_b32 m0, s36
	s_add_u32 s72, s26, 0x40000
	ds_read_b128 v[58:61], v226 offset:16384
	ds_read_b128 v[62:65], v226 offset:17408
	ds_read_b128 v[50:53], v226 offset:18432
	ds_read_b128 v[54:57], v226 offset:19456
	ds_read_b128 v[42:45], v226 offset:20480
	ds_read_b128 v[46:49], v226 offset:21504
	ds_read_b128 v[34:37], v226 offset:22528
	ds_read_b128 v[38:41], v226 offset:23552
	global_load_lds_dwordx4 v196, s[26:27]
	s_mov_b32 m0, s37
	s_addc_u32 s73, s27, 0
	global_load_lds_dwordx4 v200, s[26:27]
	s_mov_b32 m0, s38
	s_nop 0
	global_load_lds_dwordx4 v196, s[72:73]
	s_mov_b32 m0, s39
	s_andn2_b64 vcc, exec, s[30:31]
	global_load_lds_dwordx4 v200, s[72:73]
	s_mov_b32 m0, s40
	s_nop 0
	global_load_lds_dwordx4 v194, s[28:29]
	s_mov_b32 m0, s41
	s_nop 0
	global_load_lds_dwordx4 v198, s[28:29]
	s_cbranch_vccnz .LBB0_892
	s_waitcnt vmcnt(24)
	s_cbranch_execnz .LBB0_885
	s_branch .LBB0_884

.LBB0_1062:
	s_waitcnt lgkmcnt(0)
	s_barrier
	s_setprio 1
	s_waitcnt lgkmcnt(0)
	v_mfma_f32_16x16x128_f8f6f4 v[126:129], v[26:33], v[58:65], v[126:129]
	v_mfma_f32_16x16x128_f8f6f4 v[122:125], v[18:25], v[58:65], v[122:125]
	v_mfma_f32_16x16x128_f8f6f4 v[114:117], v[26:33], v[50:57], v[114:117]
	v_mfma_f32_16x16x128_f8f6f4 v[106:109], v[18:25], v[50:57], v[106:109]
	v_mfma_f32_16x16x128_f8f6f4 v[98:101], v[26:33], v[42:49], v[98:101]
	v_mfma_f32_16x16x128_f8f6f4 v[90:93], v[18:25], v[42:49], v[90:93]
	v_mfma_f32_16x16x128_f8f6f4 v[82:85], v[26:33], v[34:41], v[82:85]
	v_mfma_f32_16x16x128_f8f6f4 v[74:77], v[18:25], v[34:41], v[74:77]
	s_setprio 0
	s_setprio 1
	v_mfma_f32_16x16x128_f8f6f4 v[118:121], v[10:17], v[58:65], v[118:121]
	v_mfma_f32_16x16x128_f8f6f4 v[110:113], v[2:9], v[58:65], v[110:113]
	v_mfma_f32_16x16x128_f8f6f4 v[102:105], v[10:17], v[50:57], v[102:105]
	v_mfma_f32_16x16x128_f8f6f4 v[94:97], v[2:9], v[50:57], v[94:97]
	v_mfma_f32_16x16x128_f8f6f4 v[86:89], v[10:17], v[42:49], v[86:89]
	v_mfma_f32_16x16x128_f8f6f4 v[78:81], v[2:9], v[42:49], v[78:81]
	v_mfma_f32_16x16x128_f8f6f4 v[70:73], v[10:17], v[34:41], v[70:73]
	v_mfma_f32_16x16x128_f8f6f4 v[66:69], v[2:9], v[34:41], v[66:69]
	s_setprio 0
	s_barrier
	v_add_u32_e32 v14, s58, v222
	v_add_u32_e32 v30, s63, v222
	ds_read_b128 v[2:5], v14
	ds_read_b128 v[6:9], v14 offset:1024
	ds_read_b128 v[10:13], v14 offset:2048
	ds_read_b128 v[14:17], v14 offset:3072
	ds_read_b128 v[18:21], v30
	ds_read_b128 v[22:25], v30 offset:1024
	ds_read_b128 v[26:29], v30 offset:2048
	ds_read_b128 v[30:33], v30 offset:3072
	s_add_u32 s100, s40, 0x40000
	s_addc_u32 s101, s41, 0
	s_mov_b32 m0, s56
	ds_read_b128 v[34:37], v226 offset:32768
	ds_read_b128 v[38:41], v226 offset:33792
	ds_read_b128 v[42:45], v226 offset:34816
	ds_read_b128 v[46:49], v226 offset:35840
	ds_read_b128 v[50:53], v226 offset:36864
	ds_read_b128 v[54:57], v226 offset:37888
	ds_read_b128 v[58:61], v226 offset:38912
	ds_read_b128 v[62:65], v226 offset:39936
	global_load_lds_dwordx4 v200, s[100:101]
	s_mov_b32 m0, s57
	s_nop 0
	global_load_lds_dwordx4 v196, s[100:101]
	s_waitcnt vmcnt(8)
	s_waitcnt lgkmcnt(0)
	s_barrier
	s_setprio 1
	s_waitcnt lgkmcnt(0)
	v_mfma_f32_16x16x128_f8f6f4 v[190:193], v[2:9], v[34:41], v[190:193]
	v_mfma_f32_16x16x128_f8f6f4 v[186:189], v[10:17], v[34:41], v[186:189]
	v_mfma_f32_16x16x128_f8f6f4 v[178:181], v[2:9], v[42:49], v[178:181]
	v_mfma_f32_16x16x128_f8f6f4 v[170:173], v[10:17], v[42:49], v[170:173]
	v_mfma_f32_16x16x128_f8f6f4 v[162:165], v[2:9], v[50:57], v[162:165]
	v_mfma_f32_16x16x128_f8f6f4 v[154:157], v[10:17], v[50:57], v[154:157]
	v_mfma_f32_16x16x128_f8f6f4 v[146:149], v[2:9], v[58:65], v[146:149]
	v_mfma_f32_16x16x128_f8f6f4 v[138:141], v[10:17], v[58:65], v[138:141]
	s_setprio 0
	s_setprio 1
	v_mfma_f32_16x16x128_f8f6f4 v[182:185], v[18:25], v[34:41], v[182:185]
	v_mfma_f32_16x16x128_f8f6f4 v[174:177], v[26:33], v[34:41], v[174:177]
	v_mfma_f32_16x16x128_f8f6f4 v[166:169], v[18:25], v[42:49], v[166:169]
	v_mfma_f32_16x16x128_f8f6f4 v[158:161], v[26:33], v[42:49], v[158:161]
	v_mfma_f32_16x16x128_f8f6f4 v[150:153], v[18:25], v[50:57], v[150:153]
	v_mfma_f32_16x16x128_f8f6f4 v[142:145], v[26:33], v[50:57], v[142:145]
	v_mfma_f32_16x16x128_f8f6f4 v[134:137], v[18:25], v[58:65], v[134:137]
	v_mfma_f32_16x16x128_f8f6f4 v[130:133], v[26:33], v[58:65], v[130:133]
	s_setprio 0
	s_barrier
	s_mov_b32 m0, s59
	ds_read_b128 v[34:37], v226 offset:49152
	ds_read_b128 v[38:41], v226 offset:50176
	ds_read_b128 v[42:45], v226 offset:51200
	ds_read_b128 v[46:49], v226 offset:52224
	ds_read_b128 v[50:53], v226 offset:53248
	ds_read_b128 v[54:57], v226 offset:54272
	ds_read_b128 v[58:61], v226 offset:55296
	ds_read_b128 v[62:65], v226 offset:56320
	s_add_u32 s98, s38, 0x80
	s_addc_u32 s99, s39, 0
	global_load_lds_dwordx4 v198, s[98:99]
	s_mov_b32 m0, s60
	s_nop 0
	global_load_lds_dwordx4 v194, s[98:99]
	s_mov_b32 m0, s64
	s_nop 0
	s_add_u32 s100, s78, 0x80
	s_addc_u32 s101, s79, 0
	global_load_lds_dwordx4 v198, s[100:101]
	s_mov_b32 m0, s65
	s_nop 0
	global_load_lds_dwordx4 v194, s[100:101]
	s_mov_b32 m0, s61
	s_nop 0
	s_add_u32 s98, s40, 0x80
	s_addc_u32 s99, s41, 0
	global_load_lds_dwordx4 v200, s[98:99]
	s_mov_b32 m0, s62
	s_nop 0
	global_load_lds_dwordx4 v196, s[98:99]
	s_waitcnt vmcnt(8)
	s_waitcnt lgkmcnt(0)
	s_barrier
	s_setprio 1
	s_waitcnt lgkmcnt(0)
	v_mfma_f32_16x16x128_f8f6f4 v[126:129], v[2:9], v[34:41], v[126:129]
	v_mfma_f32_16x16x128_f8f6f4 v[122:125], v[10:17], v[34:41], v[122:125]
	v_mfma_f32_16x16x128_f8f6f4 v[114:117], v[2:9], v[42:49], v[114:117]
	v_mfma_f32_16x16x128_f8f6f4 v[106:109], v[10:17], v[42:49], v[106:109]
	v_mfma_f32_16x16x128_f8f6f4 v[98:101], v[2:9], v[50:57], v[98:101]
	v_mfma_f32_16x16x128_f8f6f4 v[90:93], v[10:17], v[50:57], v[90:93]
	v_mfma_f32_16x16x128_f8f6f4 v[82:85], v[2:9], v[58:65], v[82:85]
	v_mfma_f32_16x16x128_f8f6f4 v[74:77], v[10:17], v[58:65], v[74:77]
	s_setprio 0
	s_setprio 1
	v_mfma_f32_16x16x128_f8f6f4 v[118:121], v[18:25], v[34:41], v[118:121]
	v_mfma_f32_16x16x128_f8f6f4 v[110:113], v[26:33], v[34:41], v[110:113]
	v_mfma_f32_16x16x128_f8f6f4 v[102:105], v[18:25], v[42:49], v[102:105]
	v_mfma_f32_16x16x128_f8f6f4 v[94:97], v[26:33], v[42:49], v[94:97]
	v_mfma_f32_16x16x128_f8f6f4 v[86:89], v[18:25], v[50:57], v[86:89]
	v_mfma_f32_16x16x128_f8f6f4 v[78:81], v[26:33], v[50:57], v[78:81]
	v_mfma_f32_16x16x128_f8f6f4 v[70:73], v[18:25], v[58:65], v[70:73]
	v_mfma_f32_16x16x128_f8f6f4 v[66:69], v[26:33], v[58:65], v[66:69]
	s_setprio 0
	s_barrier
	s_add_i32 s77, s77, 2
	s_add_u32 s36, s36, 0x100
	s_addc_u32 s37, s37, 0
	s_cmp_gt_u32 s77, 13
	s_cbranch_scc1 .LBB0_1070
.LBB0_1063:
	s_cmp_eq_u32 s36, 0
	s_cselect_b64 s[38:39], -1, 0
	s_and_b64 s[38:39], s[34:35], s[38:39]
	v_cndmask_b32_e64 v2, 0, 1, s[38:39]
	s_nop 0
	v_readfirstlane_b32 s38, v2
	s_and_b32 s38, s38, 1
	ds_read_b128 v[26:29], v224
	ds_read_b128 v[30:33], v224 offset:1024
	ds_read_b128 v[18:21], v224 offset:2048
	ds_read_b128 v[22:25], v224 offset:3072
	ds_read_b128 v[10:13], v225
	ds_read_b128 v[14:17], v225 offset:1024
	ds_read_b128 v[2:5], v225 offset:2048
	ds_read_b128 v[6:9], v225 offset:3072
	s_add_u32 s98, s30, s36
	s_addc_u32 s99, s31, s37
	s_add_i32 m0, s54, 0xc000
	ds_read_b128 v[58:61], v226
	ds_read_b128 v[62:65], v226 offset:1024
	ds_read_b128 v[50:53], v226 offset:2048
	ds_read_b128 v[54:57], v226 offset:3072
	ds_read_b128 v[42:45], v226 offset:4096
	ds_read_b128 v[46:49], v226 offset:5120
	ds_read_b128 v[34:37], v226 offset:6144
	ds_read_b128 v[38:41], v226 offset:7168
	global_load_lds_dwordx4 v204, s[98:99]
	s_add_i32 m0, s54, 0xe000
	s_cmp_lg_u32 s38, 0
	global_load_lds_dwordx4 v202, s[98:99]
	s_cselect_b64 s[42:43], -1, 0
	s_cmp_eq_u32 s38, 0
	s_cbranch_scc1 .LBB0_1068
	s_waitcnt vmcnt(24)
	s_cbranch_execnz .LBB0_1066

.LBB0_1066:
	s_add_u32 s38, s30, s36
	s_addc_u32 s39, s31, s37
	s_add_u32 s38, s38, 0x100
	s_addc_u32 s39, s39, 0
	s_add_u32 s78, s75, s36
	s_addc_u32 s79, s76, s37
	s_waitcnt lgkmcnt(0)
	s_cmpk_eq_i32 s36, 0x700
	s_cselect_b32 s41, s21, s39
	s_cselect_b32 s40, s73, s38
	s_cselect_b32 s39, s23, s79
	s_cselect_b32 s38, s74, s78
	s_barrier
	s_setprio 1
	s_waitcnt lgkmcnt(0)
	v_mfma_f32_16x16x128_f8f6f4 v[190:193], v[26:33], v[58:65], v[190:193]
	v_mfma_f32_16x16x128_f8f6f4 v[186:189], v[18:25], v[58:65], v[186:189]
	v_mfma_f32_16x16x128_f8f6f4 v[178:181], v[26:33], v[50:57], v[178:181]
	v_mfma_f32_16x16x128_f8f6f4 v[170:173], v[18:25], v[50:57], v[170:173]
	v_mfma_f32_16x16x128_f8f6f4 v[162:165], v[26:33], v[42:49], v[162:165]
	v_mfma_f32_16x16x128_f8f6f4 v[154:157], v[18:25], v[42:49], v[154:157]
	v_mfma_f32_16x16x128_f8f6f4 v[146:149], v[26:33], v[34:41], v[146:149]
	v_mfma_f32_16x16x128_f8f6f4 v[138:141], v[18:25], v[34:41], v[138:141]
	s_setprio 0
	s_setprio 1
	v_mfma_f32_16x16x128_f8f6f4 v[182:185], v[10:17], v[58:65], v[182:185]
	v_mfma_f32_16x16x128_f8f6f4 v[174:177], v[2:9], v[58:65], v[174:177]
	v_mfma_f32_16x16x128_f8f6f4 v[166:169], v[10:17], v[50:57], v[166:169]
	v_mfma_f32_16x16x128_f8f6f4 v[158:161], v[2:9], v[50:57], v[158:161]
	v_mfma_f32_16x16x128_f8f6f4 v[150:153], v[10:17], v[42:49], v[150:153]
	v_mfma_f32_16x16x128_f8f6f4 v[142:145], v[2:9], v[42:49], v[142:145]
	v_mfma_f32_16x16x128_f8f6f4 v[134:137], v[10:17], v[34:41], v[134:137]
	v_mfma_f32_16x16x128_f8f6f4 v[130:133], v[2:9], v[34:41], v[130:133]
	s_setprio 0
	s_barrier
	s_mov_b32 m0, s29
	s_add_u32 s78, s38, 0x40000
	ds_read_b128 v[58:61], v226 offset:16384
	ds_read_b128 v[62:65], v226 offset:17408
	ds_read_b128 v[50:53], v226 offset:18432
	ds_read_b128 v[54:57], v226 offset:19456
	ds_read_b128 v[42:45], v226 offset:20480
	ds_read_b128 v[46:49], v226 offset:21504
	ds_read_b128 v[34:37], v226 offset:22528
	ds_read_b128 v[38:41], v226 offset:23552
	global_load_lds_dwordx4 v198, s[38:39]
	s_mov_b32 m0, s51
	s_addc_u32 s79, s39, 0
	global_load_lds_dwordx4 v194, s[38:39]
	s_mov_b32 m0, s52
	s_nop 0
	global_load_lds_dwordx4 v198, s[78:79]
	s_mov_b32 m0, s53
	s_andn2_b64 vcc, exec, s[42:43]
	global_load_lds_dwordx4 v194, s[78:79]
	s_mov_b32 m0, s54
	s_nop 0
	global_load_lds_dwordx4 v200, s[40:41]
	s_mov_b32 m0, s55
	s_nop 0
	global_load_lds_dwordx4 v196, s[40:41]
	s_cbranch_vccnz .LBB0_1069
	s_waitcnt vmcnt(24)
	s_cbranch_execnz .LBB0_1062
	s_branch .LBB0_1061

.LBB0_1225:
	s_waitcnt lgkmcnt(0)
	s_barrier
	s_setprio 1
	s_waitcnt lgkmcnt(0)
	v_mfma_f32_16x16x32_bf16 v[54:57], v[82:85], v[186:189], v[54:57]
	v_mfma_f32_16x16x32_bf16 v[46:49], v[90:93], v[186:189], v[46:49]
	v_mfma_f32_16x16x32_bf16 v[50:53], v[82:85], v[178:181], v[50:53]
	v_mfma_f32_16x16x32_bf16 v[38:41], v[90:93], v[178:181], v[38:41]
	v_mfma_f32_16x16x32_bf16 v[30:33], v[82:85], v[170:173], v[30:33]
	v_mfma_f32_16x16x32_bf16 v[22:25], v[90:93], v[170:173], v[22:25]
	v_mfma_f32_16x16x32_bf16 v[14:17], v[82:85], v[162:165], v[14:17]
	v_mfma_f32_16x16x32_bf16 v[10:13], v[90:93], v[162:165], v[10:13]
	v_mfma_f32_16x16x32_bf16 v[54:57], v[86:89], v[190:193], v[54:57]
	v_mfma_f32_16x16x32_bf16 v[46:49], v[94:97], v[190:193], v[46:49]
	v_mfma_f32_16x16x32_bf16 v[50:53], v[86:89], v[182:185], v[50:53]
	v_mfma_f32_16x16x32_bf16 v[38:41], v[94:97], v[182:185], v[38:41]
	v_mfma_f32_16x16x32_bf16 v[30:33], v[86:89], v[174:177], v[30:33]
	v_mfma_f32_16x16x32_bf16 v[22:25], v[94:97], v[174:177], v[22:25]
	v_mfma_f32_16x16x32_bf16 v[14:17], v[86:89], v[166:169], v[14:17]
	v_mfma_f32_16x16x32_bf16 v[10:13], v[94:97], v[166:169], v[10:13]
	s_setprio 0
	s_setprio 1
	v_mfma_f32_16x16x32_bf16 v[62:65], v[66:69], v[186:189], v[62:65]
	v_mfma_f32_16x16x32_bf16 v[58:61], v[74:77], v[186:189], v[58:61]
	v_mfma_f32_16x16x32_bf16 v[42:45], v[66:69], v[178:181], v[42:45]
	v_mfma_f32_16x16x32_bf16 v[34:37], v[74:77], v[178:181], v[34:37]
	v_mfma_f32_16x16x32_bf16 v[26:29], v[66:69], v[170:173], v[26:29]
	v_mfma_f32_16x16x32_bf16 v[18:21], v[74:77], v[170:173], v[18:21]
	v_mfma_f32_16x16x32_bf16 v[6:9], v[66:69], v[162:165], v[6:9]
	v_mfma_f32_16x16x32_bf16 v[2:5], v[74:77], v[162:165], v[2:5]
	v_mfma_f32_16x16x32_bf16 v[62:65], v[70:73], v[190:193], v[62:65]
	v_mfma_f32_16x16x32_bf16 v[58:61], v[78:81], v[190:193], v[58:61]
	v_mfma_f32_16x16x32_bf16 v[42:45], v[70:73], v[182:185], v[42:45]
	v_mfma_f32_16x16x32_bf16 v[34:37], v[78:81], v[182:185], v[34:37]
	v_mfma_f32_16x16x32_bf16 v[26:29], v[70:73], v[174:177], v[26:29]
	v_mfma_f32_16x16x32_bf16 v[18:21], v[78:81], v[174:177], v[18:21]
	v_mfma_f32_16x16x32_bf16 v[6:9], v[70:73], v[166:169], v[6:9]
	v_mfma_f32_16x16x32_bf16 v[2:5], v[78:81], v[166:169], v[2:5]
	s_setprio 0
	s_barrier
	v_add_u32_e32 v78, s74, v1
	v_add_u32_e32 v94, s79, v1
	ds_read_b128 v[66:69], v78
	ds_read_b128 v[70:73], v78 offset:1024
	ds_read_b128 v[74:77], v78 offset:2048
	ds_read_b128 v[78:81], v78 offset:3072
	ds_read_b128 v[82:85], v94
	ds_read_b128 v[86:89], v94 offset:1024
	ds_read_b128 v[90:93], v94 offset:2048
	ds_read_b128 v[94:97], v94 offset:3072
	s_add_u32 s100, s54, 0x80000
	s_addc_u32 s101, s55, 0
	s_mov_b32 m0, s70
	ds_read_b128 v[162:165], v231 offset:32768
	ds_read_b128 v[166:169], v231 offset:33792
	ds_read_b128 v[170:173], v231 offset:34816
	ds_read_b128 v[174:177], v231 offset:35840
	ds_read_b128 v[178:181], v231 offset:36864
	ds_read_b128 v[182:185], v231 offset:37888
	ds_read_b128 v[186:189], v231 offset:38912
	ds_read_b128 v[190:193], v231 offset:39936
	global_load_lds_dwordx4 v194, s[100:101]
	s_mov_b32 m0, s71
	s_nop 0
	global_load_lds_dwordx4 v198, s[100:101]
	s_waitcnt vmcnt(8)
	s_waitcnt lgkmcnt(0)
	s_barrier
	s_setprio 1
	s_waitcnt lgkmcnt(0)
	v_mfma_f32_16x16x32_bf16 v[150:153], v[66:69], v[162:165], v[150:153]
	v_mfma_f32_16x16x32_bf16 v[142:145], v[74:77], v[162:165], v[142:145]
	v_mfma_f32_16x16x32_bf16 v[146:149], v[66:69], v[170:173], v[146:149]
	v_mfma_f32_16x16x32_bf16 v[134:137], v[74:77], v[170:173], v[134:137]
	v_mfma_f32_16x16x32_bf16 v[126:129], v[66:69], v[178:181], v[126:129]
	v_mfma_f32_16x16x32_bf16 v[118:121], v[74:77], v[178:181], v[118:121]
	v_mfma_f32_16x16x32_bf16 v[110:113], v[66:69], v[186:189], v[110:113]
	v_mfma_f32_16x16x32_bf16 v[106:109], v[74:77], v[186:189], v[106:109]
	v_mfma_f32_16x16x32_bf16 v[150:153], v[70:73], v[166:169], v[150:153]
	v_mfma_f32_16x16x32_bf16 v[142:145], v[78:81], v[166:169], v[142:145]
	v_mfma_f32_16x16x32_bf16 v[146:149], v[70:73], v[174:177], v[146:149]
	v_mfma_f32_16x16x32_bf16 v[134:137], v[78:81], v[174:177], v[134:137]
	v_mfma_f32_16x16x32_bf16 v[126:129], v[70:73], v[182:185], v[126:129]
	v_mfma_f32_16x16x32_bf16 v[118:121], v[78:81], v[182:185], v[118:121]
	v_mfma_f32_16x16x32_bf16 v[110:113], v[70:73], v[190:193], v[110:113]
	v_mfma_f32_16x16x32_bf16 v[106:109], v[78:81], v[190:193], v[106:109]
	s_setprio 0
	s_setprio 1
	v_mfma_f32_16x16x32_bf16 v[158:161], v[82:85], v[162:165], v[158:161]
	v_mfma_f32_16x16x32_bf16 v[154:157], v[90:93], v[162:165], v[154:157]
	v_mfma_f32_16x16x32_bf16 v[138:141], v[82:85], v[170:173], v[138:141]
	v_mfma_f32_16x16x32_bf16 v[130:133], v[90:93], v[170:173], v[130:133]
	v_mfma_f32_16x16x32_bf16 v[122:125], v[82:85], v[178:181], v[122:125]
	v_mfma_f32_16x16x32_bf16 v[114:117], v[90:93], v[178:181], v[114:117]
	v_mfma_f32_16x16x32_bf16 v[102:105], v[82:85], v[186:189], v[102:105]
	v_mfma_f32_16x16x32_bf16 v[98:101], v[90:93], v[186:189], v[98:101]
	v_mfma_f32_16x16x32_bf16 v[158:161], v[86:89], v[166:169], v[158:161]
	v_mfma_f32_16x16x32_bf16 v[154:157], v[94:97], v[166:169], v[154:157]
	v_mfma_f32_16x16x32_bf16 v[138:141], v[86:89], v[174:177], v[138:141]
	v_mfma_f32_16x16x32_bf16 v[130:133], v[94:97], v[174:177], v[130:133]
	v_mfma_f32_16x16x32_bf16 v[122:125], v[86:89], v[182:185], v[122:125]
	v_mfma_f32_16x16x32_bf16 v[114:117], v[94:97], v[182:185], v[114:117]
	v_mfma_f32_16x16x32_bf16 v[102:105], v[86:89], v[190:193], v[102:105]
	v_mfma_f32_16x16x32_bf16 v[98:101], v[94:97], v[190:193], v[98:101]
	s_setprio 0
	s_barrier
	s_mov_b32 m0, s75
	ds_read_b128 v[162:165], v231 offset:49152
	ds_read_b128 v[166:169], v231 offset:50176
	ds_read_b128 v[170:173], v231 offset:51200
	ds_read_b128 v[174:177], v231 offset:52224
	ds_read_b128 v[178:181], v231 offset:53248
	ds_read_b128 v[182:185], v231 offset:54272
	ds_read_b128 v[186:189], v231 offset:55296
	ds_read_b128 v[190:193], v231 offset:56320
	s_add_u32 s98, s52, 0x80
	s_addc_u32 s99, s53, 0
	global_load_lds_dwordx4 v196, s[98:99]
	s_mov_b32 m0, s76
	s_nop 0
	global_load_lds_dwordx4 v200, s[98:99]
	s_mov_b32 m0, s80
	s_nop 0
	s_add_u32 s100, s94, 0x80
	s_addc_u32 s101, s95, 0
	global_load_lds_dwordx4 v196, s[100:101]
	s_mov_b32 m0, s81
	s_nop 0
	global_load_lds_dwordx4 v200, s[100:101]
	s_mov_b32 m0, s77
	s_nop 0
	s_add_u32 s98, s54, 0x80
	s_addc_u32 s99, s55, 0
	global_load_lds_dwordx4 v194, s[98:99]
	s_mov_b32 m0, s78
	s_nop 0
	global_load_lds_dwordx4 v198, s[98:99]
	s_waitcnt vmcnt(8)
	s_waitcnt lgkmcnt(0)
	s_barrier
	s_setprio 1
	s_waitcnt lgkmcnt(0)
	v_mfma_f32_16x16x32_bf16 v[54:57], v[66:69], v[162:165], v[54:57]
	v_mfma_f32_16x16x32_bf16 v[46:49], v[74:77], v[162:165], v[46:49]
	v_mfma_f32_16x16x32_bf16 v[50:53], v[66:69], v[170:173], v[50:53]
	v_mfma_f32_16x16x32_bf16 v[38:41], v[74:77], v[170:173], v[38:41]
	v_mfma_f32_16x16x32_bf16 v[30:33], v[66:69], v[178:181], v[30:33]
	v_mfma_f32_16x16x32_bf16 v[22:25], v[74:77], v[178:181], v[22:25]
	v_mfma_f32_16x16x32_bf16 v[14:17], v[66:69], v[186:189], v[14:17]
	v_mfma_f32_16x16x32_bf16 v[10:13], v[74:77], v[186:189], v[10:13]
	v_mfma_f32_16x16x32_bf16 v[54:57], v[70:73], v[166:169], v[54:57]
	v_mfma_f32_16x16x32_bf16 v[46:49], v[78:81], v[166:169], v[46:49]
	v_mfma_f32_16x16x32_bf16 v[50:53], v[70:73], v[174:177], v[50:53]
	v_mfma_f32_16x16x32_bf16 v[38:41], v[78:81], v[174:177], v[38:41]
	v_mfma_f32_16x16x32_bf16 v[30:33], v[70:73], v[182:185], v[30:33]
	v_mfma_f32_16x16x32_bf16 v[22:25], v[78:81], v[182:185], v[22:25]
	v_mfma_f32_16x16x32_bf16 v[14:17], v[70:73], v[190:193], v[14:17]
	v_mfma_f32_16x16x32_bf16 v[10:13], v[78:81], v[190:193], v[10:13]
	s_setprio 0
	s_setprio 1
	v_mfma_f32_16x16x32_bf16 v[62:65], v[82:85], v[162:165], v[62:65]
	v_mfma_f32_16x16x32_bf16 v[58:61], v[90:93], v[162:165], v[58:61]
	v_mfma_f32_16x16x32_bf16 v[42:45], v[82:85], v[170:173], v[42:45]
	v_mfma_f32_16x16x32_bf16 v[34:37], v[90:93], v[170:173], v[34:37]
	v_mfma_f32_16x16x32_bf16 v[26:29], v[82:85], v[178:181], v[26:29]
	v_mfma_f32_16x16x32_bf16 v[18:21], v[90:93], v[178:181], v[18:21]
	v_mfma_f32_16x16x32_bf16 v[6:9], v[82:85], v[186:189], v[6:9]
	v_mfma_f32_16x16x32_bf16 v[2:5], v[90:93], v[186:189], v[2:5]
	v_mfma_f32_16x16x32_bf16 v[62:65], v[86:89], v[166:169], v[62:65]
	v_mfma_f32_16x16x32_bf16 v[58:61], v[94:97], v[166:169], v[58:61]
	v_mfma_f32_16x16x32_bf16 v[42:45], v[86:89], v[174:177], v[42:45]
	v_mfma_f32_16x16x32_bf16 v[34:37], v[94:97], v[174:177], v[34:37]
	v_mfma_f32_16x16x32_bf16 v[26:29], v[86:89], v[182:185], v[26:29]
	v_mfma_f32_16x16x32_bf16 v[18:21], v[94:97], v[182:185], v[18:21]
	v_mfma_f32_16x16x32_bf16 v[6:9], v[86:89], v[190:193], v[6:9]
	v_mfma_f32_16x16x32_bf16 v[2:5], v[94:97], v[190:193], v[2:5]
	s_setprio 0
	s_barrier
	s_add_i32 s93, s93, 2
	s_add_u32 s50, s50, 0x100
	s_addc_u32 s51, s51, 0
	s_cmp_gt_u32 s93, 29
	s_cbranch_scc1 .LBB0_1233
.LBB0_1226:
	s_cmp_eq_u32 s50, 0
	s_cselect_b64 s[52:53], -1, 0
	s_and_b64 s[52:53], s[48:49], s[52:53]
	v_cndmask_b32_e64 v66, 0, 1, s[52:53]
	s_nop 0
	v_readfirstlane_b32 s52, v66
	s_and_b32 s52, s52, 1
	ds_read_b128 v[82:85], v228
	ds_read_b128 v[86:89], v228 offset:1024
	ds_read_b128 v[90:93], v228 offset:2048
	ds_read_b128 v[94:97], v228 offset:3072
	ds_read_b128 v[66:69], v229
	ds_read_b128 v[70:73], v229 offset:1024
	ds_read_b128 v[74:77], v229 offset:2048
	ds_read_b128 v[78:81], v229 offset:3072
	s_add_u32 s98, s46, s50
	s_addc_u32 s99, s47, s51
	s_add_i32 m0, s68, 0xc000
	ds_read_b128 v[186:189], v231
	ds_read_b128 v[190:193], v231 offset:1024
	ds_read_b128 v[178:181], v231 offset:2048
	ds_read_b128 v[182:185], v231 offset:3072
	ds_read_b128 v[170:173], v231 offset:4096
	ds_read_b128 v[174:177], v231 offset:5120
	ds_read_b128 v[162:165], v231 offset:6144
	ds_read_b128 v[166:169], v231 offset:7168
	global_load_lds_dwordx4 v210, s[98:99]
	s_add_i32 m0, s68, 0xe000
	s_cmp_lg_u32 s52, 0
	global_load_lds_dwordx4 v208, s[98:99]
	s_cselect_b64 s[56:57], -1, 0
	s_cmp_eq_u32 s52, 0
	s_cbranch_scc1 .LBB0_1231
	s_waitcnt vmcnt(24)
	s_cbranch_execnz .LBB0_1229

.LBB0_1229:
	s_add_u32 s52, s46, s50
	s_addc_u32 s53, s47, s51
	s_add_u32 s52, s52, 0x100
	s_addc_u32 s53, s53, 0
	s_add_u32 s94, s91, s50
	s_addc_u32 s95, s92, s51
	s_waitcnt lgkmcnt(0)
	s_cmpk_eq_i32 s50, 0xf00
	s_cselect_b32 s55, s35, s53
	s_cselect_b32 s54, s43, s52
	s_cselect_b32 s53, s37, s95
	s_cselect_b32 s52, s45, s94
	s_barrier
	s_setprio 1
	s_waitcnt lgkmcnt(0)
	v_mfma_f32_16x16x32_bf16 v[150:153], v[82:85], v[186:189], v[150:153]
	v_mfma_f32_16x16x32_bf16 v[142:145], v[90:93], v[186:189], v[142:145]
	v_mfma_f32_16x16x32_bf16 v[146:149], v[82:85], v[178:181], v[146:149]
	v_mfma_f32_16x16x32_bf16 v[134:137], v[90:93], v[178:181], v[134:137]
	v_mfma_f32_16x16x32_bf16 v[126:129], v[82:85], v[170:173], v[126:129]
	v_mfma_f32_16x16x32_bf16 v[118:121], v[90:93], v[170:173], v[118:121]
	v_mfma_f32_16x16x32_bf16 v[110:113], v[82:85], v[162:165], v[110:113]
	v_mfma_f32_16x16x32_bf16 v[106:109], v[90:93], v[162:165], v[106:109]
	v_mfma_f32_16x16x32_bf16 v[150:153], v[86:89], v[190:193], v[150:153]
	v_mfma_f32_16x16x32_bf16 v[142:145], v[94:97], v[190:193], v[142:145]
	v_mfma_f32_16x16x32_bf16 v[146:149], v[86:89], v[182:185], v[146:149]
	v_mfma_f32_16x16x32_bf16 v[134:137], v[94:97], v[182:185], v[134:137]
	v_mfma_f32_16x16x32_bf16 v[126:129], v[86:89], v[174:177], v[126:129]
	v_mfma_f32_16x16x32_bf16 v[118:121], v[94:97], v[174:177], v[118:121]
	v_mfma_f32_16x16x32_bf16 v[110:113], v[86:89], v[166:169], v[110:113]
	v_mfma_f32_16x16x32_bf16 v[106:109], v[94:97], v[166:169], v[106:109]
	s_setprio 0
	s_setprio 1
	v_mfma_f32_16x16x32_bf16 v[158:161], v[66:69], v[186:189], v[158:161]
	v_mfma_f32_16x16x32_bf16 v[154:157], v[74:77], v[186:189], v[154:157]
	v_mfma_f32_16x16x32_bf16 v[138:141], v[66:69], v[178:181], v[138:141]
	v_mfma_f32_16x16x32_bf16 v[130:133], v[74:77], v[178:181], v[130:133]
	v_mfma_f32_16x16x32_bf16 v[122:125], v[66:69], v[170:173], v[122:125]
	v_mfma_f32_16x16x32_bf16 v[114:117], v[74:77], v[170:173], v[114:117]
	v_mfma_f32_16x16x32_bf16 v[102:105], v[66:69], v[162:165], v[102:105]
	v_mfma_f32_16x16x32_bf16 v[98:101], v[74:77], v[162:165], v[98:101]
	v_mfma_f32_16x16x32_bf16 v[158:161], v[70:73], v[190:193], v[158:161]
	v_mfma_f32_16x16x32_bf16 v[154:157], v[78:81], v[190:193], v[154:157]
	v_mfma_f32_16x16x32_bf16 v[138:141], v[70:73], v[182:185], v[138:141]
	v_mfma_f32_16x16x32_bf16 v[130:133], v[78:81], v[182:185], v[130:133]
	v_mfma_f32_16x16x32_bf16 v[122:125], v[70:73], v[174:177], v[122:125]
	v_mfma_f32_16x16x32_bf16 v[114:117], v[78:81], v[174:177], v[114:117]
	v_mfma_f32_16x16x32_bf16 v[102:105], v[70:73], v[166:169], v[102:105]
	v_mfma_f32_16x16x32_bf16 v[98:101], v[78:81], v[166:169], v[98:101]
	s_setprio 0
	s_barrier
	s_mov_b32 m0, s64
	s_add_u32 s94, s52, 0x80000
	ds_read_b128 v[186:189], v231 offset:16384
	ds_read_b128 v[190:193], v231 offset:17408
	ds_read_b128 v[178:181], v231 offset:18432
	ds_read_b128 v[182:185], v231 offset:19456
	ds_read_b128 v[170:173], v231 offset:20480
	ds_read_b128 v[174:177], v231 offset:21504
	ds_read_b128 v[162:165], v231 offset:22528
	ds_read_b128 v[166:169], v231 offset:23552
	global_load_lds_dwordx4 v196, s[52:53]
	s_mov_b32 m0, s65
	s_addc_u32 s95, s53, 0
	global_load_lds_dwordx4 v200, s[52:53]
	s_mov_b32 m0, s66
	s_nop 0
	global_load_lds_dwordx4 v196, s[94:95]
	s_mov_b32 m0, s67
	s_andn2_b64 vcc, exec, s[56:57]
	global_load_lds_dwordx4 v200, s[94:95]
	s_mov_b32 m0, s68
	s_nop 0
	global_load_lds_dwordx4 v194, s[54:55]
	s_mov_b32 m0, s69
	s_nop 0
	global_load_lds_dwordx4 v198, s[54:55]
	s_cbranch_vccnz .LBB0_1232
	s_waitcnt vmcnt(24)
	s_cbranch_execnz .LBB0_1225
	s_branch .LBB0_1224

.LBB0_1397:
	s_waitcnt lgkmcnt(0)
	s_barrier
	s_setprio 1
	s_waitcnt lgkmcnt(0)
	v_mfma_f32_16x16x32_bf16 v[62:65], v[146:149], v[186:189], v[62:65]
	v_mfma_f32_16x16x32_bf16 v[58:61], v[154:157], v[186:189], v[58:61]
	v_mfma_f32_16x16x32_bf16 v[54:57], v[146:149], v[178:181], v[54:57]
	v_mfma_f32_16x16x32_bf16 v[46:49], v[154:157], v[178:181], v[46:49]
	v_mfma_f32_16x16x32_bf16 v[38:41], v[146:149], v[170:173], v[38:41]
	v_mfma_f32_16x16x32_bf16 v[30:33], v[154:157], v[170:173], v[30:33]
	v_mfma_f32_16x16x32_bf16 v[22:25], v[146:149], v[162:165], v[22:25]
	v_mfma_f32_16x16x32_bf16 v[14:17], v[154:157], v[162:165], v[14:17]
	v_mfma_f32_16x16x32_bf16 v[62:65], v[150:153], v[190:193], v[62:65]
	v_mfma_f32_16x16x32_bf16 v[58:61], v[158:161], v[190:193], v[58:61]
	v_mfma_f32_16x16x32_bf16 v[54:57], v[150:153], v[182:185], v[54:57]
	v_mfma_f32_16x16x32_bf16 v[46:49], v[158:161], v[182:185], v[46:49]
	v_mfma_f32_16x16x32_bf16 v[38:41], v[150:153], v[174:177], v[38:41]
	v_mfma_f32_16x16x32_bf16 v[30:33], v[158:161], v[174:177], v[30:33]
	v_mfma_f32_16x16x32_bf16 v[22:25], v[150:153], v[166:169], v[22:25]
	v_mfma_f32_16x16x32_bf16 v[14:17], v[158:161], v[166:169], v[14:17]
	s_setprio 0
	s_setprio 1
	v_mfma_f32_16x16x32_bf16 v[50:53], v[130:133], v[186:189], v[50:53]
	v_mfma_f32_16x16x32_bf16 v[42:45], v[138:141], v[186:189], v[42:45]
	v_mfma_f32_16x16x32_bf16 v[34:37], v[130:133], v[178:181], v[34:37]
	v_mfma_f32_16x16x32_bf16 v[26:29], v[138:141], v[178:181], v[26:29]
	v_mfma_f32_16x16x32_bf16 v[18:21], v[130:133], v[170:173], v[18:21]
	v_mfma_f32_16x16x32_bf16 v[10:13], v[138:141], v[170:173], v[10:13]
	v_mfma_f32_16x16x32_bf16 v[6:9], v[130:133], v[162:165], v[6:9]
	v_mfma_f32_16x16x32_bf16 v[2:5], v[138:141], v[162:165], v[2:5]
	v_mfma_f32_16x16x32_bf16 v[50:53], v[134:137], v[190:193], v[50:53]
	v_mfma_f32_16x16x32_bf16 v[42:45], v[142:145], v[190:193], v[42:45]
	v_mfma_f32_16x16x32_bf16 v[34:37], v[134:137], v[182:185], v[34:37]
	v_mfma_f32_16x16x32_bf16 v[26:29], v[142:145], v[182:185], v[26:29]
	v_mfma_f32_16x16x32_bf16 v[18:21], v[134:137], v[174:177], v[18:21]
	v_mfma_f32_16x16x32_bf16 v[10:13], v[142:145], v[174:177], v[10:13]
	v_mfma_f32_16x16x32_bf16 v[6:9], v[134:137], v[166:169], v[6:9]
	v_mfma_f32_16x16x32_bf16 v[2:5], v[142:145], v[166:169], v[2:5]
	s_setprio 0
	s_barrier
	v_add_u32_e32 v142, s52, v222
	v_add_u32_e32 v158, s57, v222
	ds_read_b128 v[130:133], v142
	ds_read_b128 v[134:137], v142 offset:1024
	ds_read_b128 v[138:141], v142 offset:2048
	ds_read_b128 v[142:145], v142 offset:3072
	ds_read_b128 v[146:149], v158
	ds_read_b128 v[150:153], v158 offset:1024
	ds_read_b128 v[154:157], v158 offset:2048
	ds_read_b128 v[158:161], v158 offset:3072
	s_add_u32 s100, s30, 0x160000
	s_addc_u32 s101, s31, 0
	s_mov_b32 m0, s50
	ds_read_b128 v[162:165], v226 offset:32768
	ds_read_b128 v[166:169], v226 offset:33792
	ds_read_b128 v[170:173], v226 offset:34816
	ds_read_b128 v[174:177], v226 offset:35840
	ds_read_b128 v[178:181], v226 offset:36864
	ds_read_b128 v[182:185], v226 offset:37888
	ds_read_b128 v[186:189], v226 offset:38912
	ds_read_b128 v[190:193], v226 offset:39936
	global_load_lds_dwordx4 v200, s[100:101]
	s_mov_b32 m0, s51
	s_nop 0
	global_load_lds_dwordx4 v196, s[100:101]
	s_waitcnt vmcnt(8)
	s_waitcnt lgkmcnt(0)
	s_barrier
	s_setprio 1
	s_waitcnt lgkmcnt(0)
	v_mfma_f32_16x16x32_bf16 v[126:129], v[130:133], v[162:165], v[126:129]
	v_mfma_f32_16x16x32_bf16 v[122:125], v[138:141], v[162:165], v[122:125]
	v_mfma_f32_16x16x32_bf16 v[118:121], v[130:133], v[170:173], v[118:121]
	v_mfma_f32_16x16x32_bf16 v[110:113], v[138:141], v[170:173], v[110:113]
	v_mfma_f32_16x16x32_bf16 v[102:105], v[130:133], v[178:181], v[102:105]
	v_mfma_f32_16x16x32_bf16 v[94:97], v[138:141], v[178:181], v[94:97]
	v_mfma_f32_16x16x32_bf16 v[86:89], v[130:133], v[186:189], v[86:89]
	v_mfma_f32_16x16x32_bf16 v[78:81], v[138:141], v[186:189], v[78:81]
	v_mfma_f32_16x16x32_bf16 v[126:129], v[134:137], v[166:169], v[126:129]
	v_mfma_f32_16x16x32_bf16 v[122:125], v[142:145], v[166:169], v[122:125]
	v_mfma_f32_16x16x32_bf16 v[118:121], v[134:137], v[174:177], v[118:121]
	v_mfma_f32_16x16x32_bf16 v[110:113], v[142:145], v[174:177], v[110:113]
	v_mfma_f32_16x16x32_bf16 v[102:105], v[134:137], v[182:185], v[102:105]
	v_mfma_f32_16x16x32_bf16 v[94:97], v[142:145], v[182:185], v[94:97]
	v_mfma_f32_16x16x32_bf16 v[86:89], v[134:137], v[190:193], v[86:89]
	v_mfma_f32_16x16x32_bf16 v[78:81], v[142:145], v[190:193], v[78:81]
	s_setprio 0
	s_setprio 1
	v_mfma_f32_16x16x32_bf16 v[114:117], v[146:149], v[162:165], v[114:117]
	v_mfma_f32_16x16x32_bf16 v[106:109], v[154:157], v[162:165], v[106:109]
	v_mfma_f32_16x16x32_bf16 v[98:101], v[146:149], v[170:173], v[98:101]
	v_mfma_f32_16x16x32_bf16 v[90:93], v[154:157], v[170:173], v[90:93]
	v_mfma_f32_16x16x32_bf16 v[82:85], v[146:149], v[178:181], v[82:85]
	v_mfma_f32_16x16x32_bf16 v[74:77], v[154:157], v[178:181], v[74:77]
	v_mfma_f32_16x16x32_bf16 v[70:73], v[146:149], v[186:189], v[70:73]
	v_mfma_f32_16x16x32_bf16 v[66:69], v[154:157], v[186:189], v[66:69]
	v_mfma_f32_16x16x32_bf16 v[114:117], v[150:153], v[166:169], v[114:117]
	v_mfma_f32_16x16x32_bf16 v[106:109], v[158:161], v[166:169], v[106:109]
	v_mfma_f32_16x16x32_bf16 v[98:101], v[150:153], v[174:177], v[98:101]
	v_mfma_f32_16x16x32_bf16 v[90:93], v[158:161], v[174:177], v[90:93]
	v_mfma_f32_16x16x32_bf16 v[82:85], v[150:153], v[182:185], v[82:85]
	v_mfma_f32_16x16x32_bf16 v[74:77], v[158:161], v[182:185], v[74:77]
	v_mfma_f32_16x16x32_bf16 v[70:73], v[150:153], v[190:193], v[70:73]
	v_mfma_f32_16x16x32_bf16 v[66:69], v[158:161], v[190:193], v[66:69]
	s_setprio 0
	s_barrier
	s_mov_b32 m0, s53
	ds_read_b128 v[162:165], v226 offset:49152
	ds_read_b128 v[166:169], v226 offset:50176
	ds_read_b128 v[170:173], v226 offset:51200
	ds_read_b128 v[174:177], v226 offset:52224
	ds_read_b128 v[178:181], v226 offset:53248
	ds_read_b128 v[182:185], v226 offset:54272
	ds_read_b128 v[186:189], v226 offset:55296
	ds_read_b128 v[190:193], v226 offset:56320
	s_add_u32 s98, s28, 0x80
	s_addc_u32 s99, s29, 0
	global_load_lds_dwordx4 v198, s[98:99]
	s_mov_b32 m0, s54
	s_nop 0
	global_load_lds_dwordx4 v194, s[98:99]
	s_mov_b32 m0, s58
	s_nop 0
	s_add_u32 s100, s74, 0x80
	s_addc_u32 s101, s75, 0
	global_load_lds_dwordx4 v198, s[100:101]
	s_mov_b32 m0, s59
	s_nop 0
	global_load_lds_dwordx4 v194, s[100:101]
	s_mov_b32 m0, s55
	s_nop 0
	s_add_u32 s98, s30, 0x80
	s_addc_u32 s99, s31, 0
	global_load_lds_dwordx4 v200, s[98:99]
	s_mov_b32 m0, s56
	s_nop 0
	global_load_lds_dwordx4 v196, s[98:99]
	s_waitcnt vmcnt(8)
	s_waitcnt lgkmcnt(0)
	s_barrier
	s_setprio 1
	s_waitcnt lgkmcnt(0)
	v_mfma_f32_16x16x32_bf16 v[62:65], v[130:133], v[162:165], v[62:65]
	v_mfma_f32_16x16x32_bf16 v[58:61], v[138:141], v[162:165], v[58:61]
	v_mfma_f32_16x16x32_bf16 v[54:57], v[130:133], v[170:173], v[54:57]
	v_mfma_f32_16x16x32_bf16 v[46:49], v[138:141], v[170:173], v[46:49]
	v_mfma_f32_16x16x32_bf16 v[38:41], v[130:133], v[178:181], v[38:41]
	v_mfma_f32_16x16x32_bf16 v[30:33], v[138:141], v[178:181], v[30:33]
	v_mfma_f32_16x16x32_bf16 v[22:25], v[130:133], v[186:189], v[22:25]
	v_mfma_f32_16x16x32_bf16 v[14:17], v[138:141], v[186:189], v[14:17]
	v_mfma_f32_16x16x32_bf16 v[62:65], v[134:137], v[166:169], v[62:65]
	v_mfma_f32_16x16x32_bf16 v[58:61], v[142:145], v[166:169], v[58:61]
	v_mfma_f32_16x16x32_bf16 v[54:57], v[134:137], v[174:177], v[54:57]
	v_mfma_f32_16x16x32_bf16 v[46:49], v[142:145], v[174:177], v[46:49]
	v_mfma_f32_16x16x32_bf16 v[38:41], v[134:137], v[182:185], v[38:41]
	v_mfma_f32_16x16x32_bf16 v[30:33], v[142:145], v[182:185], v[30:33]
	v_mfma_f32_16x16x32_bf16 v[22:25], v[134:137], v[190:193], v[22:25]
	v_mfma_f32_16x16x32_bf16 v[14:17], v[142:145], v[190:193], v[14:17]
	s_setprio 0
	s_setprio 1
	v_mfma_f32_16x16x32_bf16 v[50:53], v[146:149], v[162:165], v[50:53]
	v_mfma_f32_16x16x32_bf16 v[42:45], v[154:157], v[162:165], v[42:45]
	v_mfma_f32_16x16x32_bf16 v[34:37], v[146:149], v[170:173], v[34:37]
	v_mfma_f32_16x16x32_bf16 v[26:29], v[154:157], v[170:173], v[26:29]
	v_mfma_f32_16x16x32_bf16 v[18:21], v[146:149], v[178:181], v[18:21]
	v_mfma_f32_16x16x32_bf16 v[10:13], v[154:157], v[178:181], v[10:13]
	v_mfma_f32_16x16x32_bf16 v[6:9], v[146:149], v[186:189], v[6:9]
	v_mfma_f32_16x16x32_bf16 v[2:5], v[154:157], v[186:189], v[2:5]
	v_mfma_f32_16x16x32_bf16 v[50:53], v[150:153], v[166:169], v[50:53]
	v_mfma_f32_16x16x32_bf16 v[42:45], v[158:161], v[166:169], v[42:45]
	v_mfma_f32_16x16x32_bf16 v[34:37], v[150:153], v[174:177], v[34:37]
	v_mfma_f32_16x16x32_bf16 v[26:29], v[158:161], v[174:177], v[26:29]
	v_mfma_f32_16x16x32_bf16 v[18:21], v[150:153], v[182:185], v[18:21]
	v_mfma_f32_16x16x32_bf16 v[10:13], v[158:161], v[182:185], v[10:13]
	v_mfma_f32_16x16x32_bf16 v[6:9], v[150:153], v[190:193], v[6:9]
	v_mfma_f32_16x16x32_bf16 v[2:5], v[158:161], v[190:193], v[2:5]
	s_setprio 0
	s_barrier
	s_add_i32 s72, s72, 2
	s_add_u32 s26, s26, 0x100
	s_addc_u32 s27, s27, 0
	s_cmpk_gt_u32 s72, 0x55
	s_cbranch_scc1 .LBB0_1405
.LBB0_1398:
	s_cmp_eq_u32 s26, 0
	s_cselect_b64 s[28:29], -1, 0
	s_and_b64 s[28:29], s[24:25], s[28:29]
	v_cndmask_b32_e64 v130, 0, 1, s[28:29]
	s_nop 0
	v_readfirstlane_b32 s28, v130
	s_and_b32 s28, s28, 1
	ds_read_b128 v[146:149], v224
	ds_read_b128 v[150:153], v224 offset:1024
	ds_read_b128 v[154:157], v224 offset:2048
	ds_read_b128 v[158:161], v224 offset:3072
	ds_read_b128 v[130:133], v225
	ds_read_b128 v[134:137], v225 offset:1024
	ds_read_b128 v[138:141], v225 offset:2048
	ds_read_b128 v[142:145], v225 offset:3072
	s_add_u32 s98, s22, s26
	s_addc_u32 s99, s23, s27
	s_add_i32 m0, s48, 0xc000
	ds_read_b128 v[186:189], v226
	ds_read_b128 v[190:193], v226 offset:1024
	ds_read_b128 v[178:181], v226 offset:2048
	ds_read_b128 v[182:185], v226 offset:3072
	ds_read_b128 v[170:173], v226 offset:4096
	ds_read_b128 v[174:177], v226 offset:5120
	ds_read_b128 v[162:165], v226 offset:6144
	ds_read_b128 v[166:169], v226 offset:7168
	global_load_lds_dwordx4 v204, s[98:99]
	s_add_i32 m0, s48, 0xe000
	s_cmp_lg_u32 s28, 0
	global_load_lds_dwordx4 v202, s[98:99]
	s_cselect_b64 s[34:35], -1, 0
	s_cmp_eq_u32 s28, 0
	s_cbranch_scc1 .LBB0_1403
	s_waitcnt vmcnt(24)
	s_cbranch_execnz .LBB0_1401

.LBB0_1401:
	s_add_u32 s28, s22, s26
	s_addc_u32 s29, s23, s27
	s_add_u32 s28, s28, 0x100
	s_addc_u32 s29, s29, 0
	s_add_u32 s73, s70, s26
	s_addc_u32 s74, s71, s27
	s_waitcnt lgkmcnt(0)
	s_cmpk_eq_i32 s26, 0x2b00
	s_cselect_b32 s31, s1, s29
	s_cselect_b32 s30, s0, s28
	s_cselect_b32 s29, s21, s74
	s_cselect_b32 s28, s20, s73
	s_barrier
	s_setprio 1
	s_waitcnt lgkmcnt(0)
	v_mfma_f32_16x16x32_bf16 v[126:129], v[146:149], v[186:189], v[126:129]
	v_mfma_f32_16x16x32_bf16 v[122:125], v[154:157], v[186:189], v[122:125]
	v_mfma_f32_16x16x32_bf16 v[118:121], v[146:149], v[178:181], v[118:121]
	v_mfma_f32_16x16x32_bf16 v[110:113], v[154:157], v[178:181], v[110:113]
	v_mfma_f32_16x16x32_bf16 v[102:105], v[146:149], v[170:173], v[102:105]
	v_mfma_f32_16x16x32_bf16 v[94:97], v[154:157], v[170:173], v[94:97]
	v_mfma_f32_16x16x32_bf16 v[86:89], v[146:149], v[162:165], v[86:89]
	v_mfma_f32_16x16x32_bf16 v[78:81], v[154:157], v[162:165], v[78:81]
	v_mfma_f32_16x16x32_bf16 v[126:129], v[150:153], v[190:193], v[126:129]
	v_mfma_f32_16x16x32_bf16 v[122:125], v[158:161], v[190:193], v[122:125]
	v_mfma_f32_16x16x32_bf16 v[118:121], v[150:153], v[182:185], v[118:121]
	v_mfma_f32_16x16x32_bf16 v[110:113], v[158:161], v[182:185], v[110:113]
	v_mfma_f32_16x16x32_bf16 v[102:105], v[150:153], v[174:177], v[102:105]
	v_mfma_f32_16x16x32_bf16 v[94:97], v[158:161], v[174:177], v[94:97]
	v_mfma_f32_16x16x32_bf16 v[86:89], v[150:153], v[166:169], v[86:89]
	v_mfma_f32_16x16x32_bf16 v[78:81], v[158:161], v[166:169], v[78:81]
	s_setprio 0
	s_setprio 1
	v_mfma_f32_16x16x32_bf16 v[114:117], v[130:133], v[186:189], v[114:117]
	v_mfma_f32_16x16x32_bf16 v[106:109], v[138:141], v[186:189], v[106:109]
	v_mfma_f32_16x16x32_bf16 v[98:101], v[130:133], v[178:181], v[98:101]
	v_mfma_f32_16x16x32_bf16 v[90:93], v[138:141], v[178:181], v[90:93]
	v_mfma_f32_16x16x32_bf16 v[82:85], v[130:133], v[170:173], v[82:85]
	v_mfma_f32_16x16x32_bf16 v[74:77], v[138:141], v[170:173], v[74:77]
	v_mfma_f32_16x16x32_bf16 v[70:73], v[130:133], v[162:165], v[70:73]
	v_mfma_f32_16x16x32_bf16 v[66:69], v[138:141], v[162:165], v[66:69]
	v_mfma_f32_16x16x32_bf16 v[114:117], v[134:137], v[190:193], v[114:117]
	v_mfma_f32_16x16x32_bf16 v[106:109], v[142:145], v[190:193], v[106:109]
	v_mfma_f32_16x16x32_bf16 v[98:101], v[134:137], v[182:185], v[98:101]
	v_mfma_f32_16x16x32_bf16 v[90:93], v[142:145], v[182:185], v[90:93]
	v_mfma_f32_16x16x32_bf16 v[82:85], v[134:137], v[174:177], v[82:85]
	v_mfma_f32_16x16x32_bf16 v[74:77], v[142:145], v[174:177], v[74:77]
	v_mfma_f32_16x16x32_bf16 v[70:73], v[134:137], v[166:169], v[70:73]
	v_mfma_f32_16x16x32_bf16 v[66:69], v[142:145], v[166:169], v[66:69]
	s_setprio 0
	s_barrier
	s_mov_b32 m0, s44
	s_add_u32 s74, s28, 0x160000
	ds_read_b128 v[186:189], v226 offset:16384
	ds_read_b128 v[190:193], v226 offset:17408
	ds_read_b128 v[178:181], v226 offset:18432
	ds_read_b128 v[182:185], v226 offset:19456
	ds_read_b128 v[170:173], v226 offset:20480
	ds_read_b128 v[174:177], v226 offset:21504
	ds_read_b128 v[162:165], v226 offset:22528
	ds_read_b128 v[166:169], v226 offset:23552
	global_load_lds_dwordx4 v198, s[28:29]
	s_mov_b32 m0, s45
	s_addc_u32 s75, s29, 0
	global_load_lds_dwordx4 v194, s[28:29]
	s_mov_b32 m0, s46
	s_nop 0
	global_load_lds_dwordx4 v198, s[74:75]
	s_mov_b32 m0, s47
	s_andn2_b64 vcc, exec, s[34:35]
	global_load_lds_dwordx4 v194, s[74:75]
	s_mov_b32 m0, s48
	s_nop 0
	global_load_lds_dwordx4 v200, s[30:31]
	s_mov_b32 m0, s49
	s_nop 0
	global_load_lds_dwordx4 v196, s[30:31]
	s_cbranch_vccnz .LBB0_1404
	s_waitcnt vmcnt(24)
	s_cbranch_execnz .LBB0_1397
	s_branch .LBB0_1396

.LBB0_2224:
	s_waitcnt lgkmcnt(0)
	s_barrier
	s_setprio 1
	s_waitcnt lgkmcnt(0)
	v_mfma_f32_16x16x128_f8f6f4 v[126:129], v[26:33], v[58:65], v[126:129]
	v_mfma_f32_16x16x128_f8f6f4 v[122:125], v[18:25], v[58:65], v[122:125]
	v_mfma_f32_16x16x128_f8f6f4 v[110:113], v[26:33], v[50:57], v[110:113]
	v_mfma_f32_16x16x128_f8f6f4 v[106:109], v[18:25], v[50:57], v[106:109]
	v_mfma_f32_16x16x128_f8f6f4 v[94:97], v[26:33], v[42:49], v[94:97]
	v_mfma_f32_16x16x128_f8f6f4 v[90:93], v[18:25], v[42:49], v[90:93]
	v_mfma_f32_16x16x128_f8f6f4 v[78:81], v[26:33], v[34:41], v[78:81]
	v_mfma_f32_16x16x128_f8f6f4 v[74:77], v[18:25], v[34:41], v[74:77]
	s_setprio 0
	s_setprio 1
	v_mfma_f32_16x16x128_f8f6f4 v[118:121], v[10:17], v[58:65], v[118:121]
	v_mfma_f32_16x16x128_f8f6f4 v[114:117], v[2:9], v[58:65], v[114:117]
	v_mfma_f32_16x16x128_f8f6f4 v[102:105], v[10:17], v[50:57], v[102:105]
	v_mfma_f32_16x16x128_f8f6f4 v[98:101], v[2:9], v[50:57], v[98:101]
	v_mfma_f32_16x16x128_f8f6f4 v[86:89], v[10:17], v[42:49], v[86:89]
	v_mfma_f32_16x16x128_f8f6f4 v[82:85], v[2:9], v[42:49], v[82:85]
	v_mfma_f32_16x16x128_f8f6f4 v[70:73], v[10:17], v[34:41], v[70:73]
	v_mfma_f32_16x16x128_f8f6f4 v[66:69], v[2:9], v[34:41], v[66:69]
	s_setprio 0
	s_barrier
	v_add_u32_e32 v14, s48, v222
	v_add_u32_e32 v30, s53, v222
	ds_read_b128 v[2:5], v14
	ds_read_b128 v[6:9], v14 offset:1024
	ds_read_b128 v[10:13], v14 offset:2048
	ds_read_b128 v[14:17], v14 offset:3072
	ds_read_b128 v[18:21], v30
	ds_read_b128 v[22:25], v30 offset:1024
	ds_read_b128 v[26:29], v30 offset:2048
	ds_read_b128 v[30:33], v30 offset:3072
	s_add_u32 s100, s28, 0x530000
	s_addc_u32 s101, s29, 0
	s_mov_b32 m0, s42
	ds_read_b128 v[34:37], v226 offset:32768
	ds_read_b128 v[38:41], v226 offset:33792
	ds_read_b128 v[42:45], v226 offset:34816
	ds_read_b128 v[46:49], v226 offset:35840
	ds_read_b128 v[50:53], v226 offset:36864
	ds_read_b128 v[54:57], v226 offset:37888
	ds_read_b128 v[58:61], v226 offset:38912
	ds_read_b128 v[62:65], v226 offset:39936
	global_load_lds_dwordx4 v194, s[100:101]
	s_mov_b32 m0, s43
	s_nop 0
	global_load_lds_dwordx4 v198, s[100:101]
	s_waitcnt vmcnt(8)
	s_waitcnt lgkmcnt(0)
	s_barrier
	s_setprio 1
	s_waitcnt lgkmcnt(0)
	v_mfma_f32_16x16x128_f8f6f4 v[190:193], v[2:9], v[34:41], v[190:193]
	v_mfma_f32_16x16x128_f8f6f4 v[186:189], v[10:17], v[34:41], v[186:189]
	v_mfma_f32_16x16x128_f8f6f4 v[174:177], v[2:9], v[42:49], v[174:177]
	v_mfma_f32_16x16x128_f8f6f4 v[170:173], v[10:17], v[42:49], v[170:173]
	v_mfma_f32_16x16x128_f8f6f4 v[158:161], v[2:9], v[50:57], v[158:161]
	v_mfma_f32_16x16x128_f8f6f4 v[154:157], v[10:17], v[50:57], v[154:157]
	v_mfma_f32_16x16x128_f8f6f4 v[142:145], v[2:9], v[58:65], v[142:145]
	v_mfma_f32_16x16x128_f8f6f4 v[138:141], v[10:17], v[58:65], v[138:141]
	s_setprio 0
	s_setprio 1
	v_mfma_f32_16x16x128_f8f6f4 v[182:185], v[18:25], v[34:41], v[182:185]
	v_mfma_f32_16x16x128_f8f6f4 v[178:181], v[26:33], v[34:41], v[178:181]
	v_mfma_f32_16x16x128_f8f6f4 v[166:169], v[18:25], v[42:49], v[166:169]
	v_mfma_f32_16x16x128_f8f6f4 v[162:165], v[26:33], v[42:49], v[162:165]
	v_mfma_f32_16x16x128_f8f6f4 v[150:153], v[18:25], v[50:57], v[150:153]
	v_mfma_f32_16x16x128_f8f6f4 v[146:149], v[26:33], v[50:57], v[146:149]
	v_mfma_f32_16x16x128_f8f6f4 v[134:137], v[18:25], v[58:65], v[134:137]
	v_mfma_f32_16x16x128_f8f6f4 v[130:133], v[26:33], v[58:65], v[130:133]
	s_setprio 0
	s_barrier
	s_mov_b32 m0, s49
	ds_read_b128 v[34:37], v226 offset:49152
	ds_read_b128 v[38:41], v226 offset:50176
	ds_read_b128 v[42:45], v226 offset:51200
	ds_read_b128 v[46:49], v226 offset:52224
	ds_read_b128 v[50:53], v226 offset:53248
	ds_read_b128 v[54:57], v226 offset:54272
	ds_read_b128 v[58:61], v226 offset:55296
	ds_read_b128 v[62:65], v226 offset:56320
	s_add_u32 s98, s26, 0x80
	s_addc_u32 s99, s27, 0
	global_load_lds_dwordx4 v196, s[98:99]
	s_mov_b32 m0, s50
	s_nop 0
	global_load_lds_dwordx4 v200, s[98:99]
	s_mov_b32 m0, s54
	s_nop 0
	s_add_u32 s100, s70, 0x80
	s_addc_u32 s101, s71, 0
	global_load_lds_dwordx4 v196, s[100:101]
	s_mov_b32 m0, s55
	s_nop 0
	global_load_lds_dwordx4 v200, s[100:101]
	s_mov_b32 m0, s51
	s_nop 0
	s_add_u32 s98, s28, 0x100
	s_addc_u32 s99, s29, 0
	global_load_lds_dwordx4 v194, s[98:99]
	s_mov_b32 m0, s52
	s_nop 0
	global_load_lds_dwordx4 v198, s[98:99]
	s_waitcnt vmcnt(8)
	s_waitcnt lgkmcnt(0)
	s_barrier
	s_setprio 1
	s_waitcnt lgkmcnt(0)
	v_mfma_f32_16x16x128_f8f6f4 v[126:129], v[2:9], v[34:41], v[126:129]
	v_mfma_f32_16x16x128_f8f6f4 v[122:125], v[10:17], v[34:41], v[122:125]
	v_mfma_f32_16x16x128_f8f6f4 v[110:113], v[2:9], v[42:49], v[110:113]
	v_mfma_f32_16x16x128_f8f6f4 v[106:109], v[10:17], v[42:49], v[106:109]
	v_mfma_f32_16x16x128_f8f6f4 v[94:97], v[2:9], v[50:57], v[94:97]
	v_mfma_f32_16x16x128_f8f6f4 v[90:93], v[10:17], v[50:57], v[90:93]
	v_mfma_f32_16x16x128_f8f6f4 v[78:81], v[2:9], v[58:65], v[78:81]
	v_mfma_f32_16x16x128_f8f6f4 v[74:77], v[10:17], v[58:65], v[74:77]
	s_setprio 0
	s_setprio 1
	v_mfma_f32_16x16x128_f8f6f4 v[118:121], v[18:25], v[34:41], v[118:121]
	v_mfma_f32_16x16x128_f8f6f4 v[114:117], v[26:33], v[34:41], v[114:117]
	v_mfma_f32_16x16x128_f8f6f4 v[102:105], v[18:25], v[42:49], v[102:105]
	v_mfma_f32_16x16x128_f8f6f4 v[98:101], v[26:33], v[42:49], v[98:101]
	v_mfma_f32_16x16x128_f8f6f4 v[86:89], v[18:25], v[50:57], v[86:89]
	v_mfma_f32_16x16x128_f8f6f4 v[82:85], v[26:33], v[50:57], v[82:85]
	v_mfma_f32_16x16x128_f8f6f4 v[70:73], v[18:25], v[58:65], v[70:73]
	v_mfma_f32_16x16x128_f8f6f4 v[66:69], v[26:33], v[58:65], v[66:69]
	s_setprio 0
	s_barrier
	s_add_i32 s69, s69, 2
	s_add_u32 s6, s6, 0x200
	s_addc_u32 s7, s7, 0
	s_add_u32 s67, s67, 0x100
	s_addc_u32 s68, s68, 0
	s_cmp_gt_u32 s69, 13
	s_cbranch_scc1 .LBB0_2232

.LBB0_2228:
	s_add_u32 s26, s4, s6
	s_addc_u32 s27, s5, s7
	s_add_u32 s26, s26, 0x200
	s_addc_u32 s27, s27, 0
	s_waitcnt lgkmcnt(0)
	s_cmpk_eq_i32 s6, 0xe00
	s_cselect_b32 s29, s23, s27
	s_cselect_b32 s28, s22, s26
	s_cselect_b32 s27, s65, s68
	s_cselect_b32 s26, s66, s67
	s_barrier
	s_setprio 1
	s_waitcnt lgkmcnt(0)
	v_mfma_f32_16x16x128_f8f6f4 v[190:193], v[26:33], v[58:65], v[190:193]
	v_mfma_f32_16x16x128_f8f6f4 v[186:189], v[18:25], v[58:65], v[186:189]
	v_mfma_f32_16x16x128_f8f6f4 v[174:177], v[26:33], v[50:57], v[174:177]
	v_mfma_f32_16x16x128_f8f6f4 v[170:173], v[18:25], v[50:57], v[170:173]
	v_mfma_f32_16x16x128_f8f6f4 v[158:161], v[26:33], v[42:49], v[158:161]
	v_mfma_f32_16x16x128_f8f6f4 v[154:157], v[18:25], v[42:49], v[154:157]
	v_mfma_f32_16x16x128_f8f6f4 v[142:145], v[26:33], v[34:41], v[142:145]
	v_mfma_f32_16x16x128_f8f6f4 v[138:141], v[18:25], v[34:41], v[138:141]
	s_setprio 0
	s_setprio 1
	v_mfma_f32_16x16x128_f8f6f4 v[182:185], v[10:17], v[58:65], v[182:185]
	v_mfma_f32_16x16x128_f8f6f4 v[178:181], v[2:9], v[58:65], v[178:181]
	v_mfma_f32_16x16x128_f8f6f4 v[166:169], v[10:17], v[50:57], v[166:169]
	v_mfma_f32_16x16x128_f8f6f4 v[162:165], v[2:9], v[50:57], v[162:165]
	v_mfma_f32_16x16x128_f8f6f4 v[150:153], v[10:17], v[42:49], v[150:153]
	v_mfma_f32_16x16x128_f8f6f4 v[146:149], v[2:9], v[42:49], v[146:149]
	v_mfma_f32_16x16x128_f8f6f4 v[134:137], v[10:17], v[34:41], v[134:137]
	v_mfma_f32_16x16x128_f8f6f4 v[130:133], v[2:9], v[34:41], v[130:133]
	s_setprio 0
	s_barrier
	s_mov_b32 m0, s36
	s_add_u32 s70, s26, 0x40000
	ds_read_b128 v[58:61], v226 offset:16384
	ds_read_b128 v[62:65], v226 offset:17408
	ds_read_b128 v[50:53], v226 offset:18432
	ds_read_b128 v[54:57], v226 offset:19456
	ds_read_b128 v[42:45], v226 offset:20480
	ds_read_b128 v[46:49], v226 offset:21504
	ds_read_b128 v[34:37], v226 offset:22528
	ds_read_b128 v[38:41], v226 offset:23552
	global_load_lds_dwordx4 v196, s[26:27]
	s_mov_b32 m0, s37
	s_addc_u32 s71, s27, 0
	global_load_lds_dwordx4 v200, s[26:27]
	s_mov_b32 m0, s38
	s_nop 0
	global_load_lds_dwordx4 v196, s[70:71]
	s_mov_b32 m0, s39
	s_andn2_b64 vcc, exec, s[30:31]
	global_load_lds_dwordx4 v200, s[70:71]
	s_mov_b32 m0, s40
	s_nop 0
	global_load_lds_dwordx4 v194, s[28:29]
	s_mov_b32 m0, s41
	s_nop 0
	global_load_lds_dwordx4 v198, s[28:29]
	s_cbranch_vccnz .LBB0_2231
	s_waitcnt vmcnt(24)
	s_cbranch_execnz .LBB0_2224
	s_branch .LBB0_2223

.LBB0_2409:
	s_waitcnt lgkmcnt(0)
	s_barrier
	s_setprio 1
	s_waitcnt lgkmcnt(0)
	v_mfma_f32_16x16x128_f8f6f4 v[126:129], v[26:33], v[58:65], v[126:129]
	v_mfma_f32_16x16x128_f8f6f4 v[122:125], v[18:25], v[58:65], v[122:125]
	v_mfma_f32_16x16x128_f8f6f4 v[114:117], v[26:33], v[50:57], v[114:117]
	v_mfma_f32_16x16x128_f8f6f4 v[106:109], v[18:25], v[50:57], v[106:109]
	v_mfma_f32_16x16x128_f8f6f4 v[98:101], v[26:33], v[42:49], v[98:101]
	v_mfma_f32_16x16x128_f8f6f4 v[90:93], v[18:25], v[42:49], v[90:93]
	v_mfma_f32_16x16x128_f8f6f4 v[82:85], v[26:33], v[34:41], v[82:85]
	v_mfma_f32_16x16x128_f8f6f4 v[74:77], v[18:25], v[34:41], v[74:77]
	s_setprio 0
	s_setprio 1
	v_mfma_f32_16x16x128_f8f6f4 v[118:121], v[10:17], v[58:65], v[118:121]
	v_mfma_f32_16x16x128_f8f6f4 v[110:113], v[2:9], v[58:65], v[110:113]
	v_mfma_f32_16x16x128_f8f6f4 v[102:105], v[10:17], v[50:57], v[102:105]
	v_mfma_f32_16x16x128_f8f6f4 v[94:97], v[2:9], v[50:57], v[94:97]
	v_mfma_f32_16x16x128_f8f6f4 v[86:89], v[10:17], v[42:49], v[86:89]
	v_mfma_f32_16x16x128_f8f6f4 v[78:81], v[2:9], v[42:49], v[78:81]
	v_mfma_f32_16x16x128_f8f6f4 v[70:73], v[10:17], v[34:41], v[70:73]
	v_mfma_f32_16x16x128_f8f6f4 v[66:69], v[2:9], v[34:41], v[66:69]
	s_setprio 0
	s_barrier
	v_add_u32_e32 v14, s57, v222
	v_add_u32_e32 v30, s62, v222
	ds_read_b128 v[2:5], v14
	ds_read_b128 v[6:9], v14 offset:1024
	ds_read_b128 v[10:13], v14 offset:2048
	ds_read_b128 v[14:17], v14 offset:3072
	ds_read_b128 v[18:21], v30
	ds_read_b128 v[22:25], v30 offset:1024
	ds_read_b128 v[26:29], v30 offset:2048
	ds_read_b128 v[30:33], v30 offset:3072
	s_add_u32 s100, s40, 0x40000
	s_addc_u32 s101, s41, 0
	s_mov_b32 m0, s55
	ds_read_b128 v[34:37], v226 offset:32768
	ds_read_b128 v[38:41], v226 offset:33792
	ds_read_b128 v[42:45], v226 offset:34816
	ds_read_b128 v[46:49], v226 offset:35840
	ds_read_b128 v[50:53], v226 offset:36864
	ds_read_b128 v[54:57], v226 offset:37888
	ds_read_b128 v[58:61], v226 offset:38912
	ds_read_b128 v[62:65], v226 offset:39936
	global_load_lds_dwordx4 v194, s[100:101]
	s_mov_b32 m0, s56
	s_nop 0
	global_load_lds_dwordx4 v198, s[100:101]
	s_waitcnt vmcnt(8)
	s_waitcnt lgkmcnt(0)
	s_barrier
	s_setprio 1
	s_waitcnt lgkmcnt(0)
	v_mfma_f32_16x16x128_f8f6f4 v[190:193], v[2:9], v[34:41], v[190:193]
	v_mfma_f32_16x16x128_f8f6f4 v[186:189], v[10:17], v[34:41], v[186:189]
	v_mfma_f32_16x16x128_f8f6f4 v[178:181], v[2:9], v[42:49], v[178:181]
	v_mfma_f32_16x16x128_f8f6f4 v[170:173], v[10:17], v[42:49], v[170:173]
	v_mfma_f32_16x16x128_f8f6f4 v[162:165], v[2:9], v[50:57], v[162:165]
	v_mfma_f32_16x16x128_f8f6f4 v[154:157], v[10:17], v[50:57], v[154:157]
	v_mfma_f32_16x16x128_f8f6f4 v[146:149], v[2:9], v[58:65], v[146:149]
	v_mfma_f32_16x16x128_f8f6f4 v[138:141], v[10:17], v[58:65], v[138:141]
	s_setprio 0
	s_setprio 1
	v_mfma_f32_16x16x128_f8f6f4 v[182:185], v[18:25], v[34:41], v[182:185]
	v_mfma_f32_16x16x128_f8f6f4 v[174:177], v[26:33], v[34:41], v[174:177]
	v_mfma_f32_16x16x128_f8f6f4 v[166:169], v[18:25], v[42:49], v[166:169]
	v_mfma_f32_16x16x128_f8f6f4 v[158:161], v[26:33], v[42:49], v[158:161]
	v_mfma_f32_16x16x128_f8f6f4 v[150:153], v[18:25], v[50:57], v[150:153]
	v_mfma_f32_16x16x128_f8f6f4 v[142:145], v[26:33], v[50:57], v[142:145]
	v_mfma_f32_16x16x128_f8f6f4 v[134:137], v[18:25], v[58:65], v[134:137]
	v_mfma_f32_16x16x128_f8f6f4 v[130:133], v[26:33], v[58:65], v[130:133]
	s_setprio 0
	s_barrier
	s_mov_b32 m0, s58
	ds_read_b128 v[34:37], v226 offset:49152
	ds_read_b128 v[38:41], v226 offset:50176
	ds_read_b128 v[42:45], v226 offset:51200
	ds_read_b128 v[46:49], v226 offset:52224
	ds_read_b128 v[50:53], v226 offset:53248
	ds_read_b128 v[54:57], v226 offset:54272
	ds_read_b128 v[58:61], v226 offset:55296
	ds_read_b128 v[62:65], v226 offset:56320
	s_add_u32 s98, s38, 0x80
	s_addc_u32 s99, s39, 0
	global_load_lds_dwordx4 v196, s[98:99]
	s_mov_b32 m0, s59
	s_nop 0
	global_load_lds_dwordx4 v200, s[98:99]
	s_mov_b32 m0, s63
	s_nop 0
	s_add_u32 s100, s78, 0x80
	s_addc_u32 s101, s79, 0
	global_load_lds_dwordx4 v196, s[100:101]
	s_mov_b32 m0, s64
	s_nop 0
	global_load_lds_dwordx4 v200, s[100:101]
	s_mov_b32 m0, s60
	s_nop 0
	s_add_u32 s98, s40, 0x80
	s_addc_u32 s99, s41, 0
	global_load_lds_dwordx4 v194, s[98:99]
	s_mov_b32 m0, s61
	s_nop 0
	global_load_lds_dwordx4 v198, s[98:99]
	s_waitcnt vmcnt(8)
	s_waitcnt lgkmcnt(0)
	s_barrier
	s_setprio 1
	s_waitcnt lgkmcnt(0)
	v_mfma_f32_16x16x128_f8f6f4 v[126:129], v[2:9], v[34:41], v[126:129]
	v_mfma_f32_16x16x128_f8f6f4 v[122:125], v[10:17], v[34:41], v[122:125]
	v_mfma_f32_16x16x128_f8f6f4 v[114:117], v[2:9], v[42:49], v[114:117]
	v_mfma_f32_16x16x128_f8f6f4 v[106:109], v[10:17], v[42:49], v[106:109]
	v_mfma_f32_16x16x128_f8f6f4 v[98:101], v[2:9], v[50:57], v[98:101]
	v_mfma_f32_16x16x128_f8f6f4 v[90:93], v[10:17], v[50:57], v[90:93]
	v_mfma_f32_16x16x128_f8f6f4 v[82:85], v[2:9], v[58:65], v[82:85]
	v_mfma_f32_16x16x128_f8f6f4 v[74:77], v[10:17], v[58:65], v[74:77]
	s_setprio 0
	s_setprio 1
	v_mfma_f32_16x16x128_f8f6f4 v[118:121], v[18:25], v[34:41], v[118:121]
	v_mfma_f32_16x16x128_f8f6f4 v[110:113], v[26:33], v[34:41], v[110:113]
	v_mfma_f32_16x16x128_f8f6f4 v[102:105], v[18:25], v[42:49], v[102:105]
	v_mfma_f32_16x16x128_f8f6f4 v[94:97], v[26:33], v[42:49], v[94:97]
	v_mfma_f32_16x16x128_f8f6f4 v[86:89], v[18:25], v[50:57], v[86:89]
	v_mfma_f32_16x16x128_f8f6f4 v[78:81], v[26:33], v[50:57], v[78:81]
	v_mfma_f32_16x16x128_f8f6f4 v[70:73], v[18:25], v[58:65], v[70:73]
	v_mfma_f32_16x16x128_f8f6f4 v[66:69], v[26:33], v[58:65], v[66:69]
	s_setprio 0
	s_barrier
	s_add_i32 s76, s76, 2
	s_add_u32 s36, s36, 0x100
	s_addc_u32 s37, s37, 0
	s_cmp_gt_u32 s76, 13
	s_cbranch_scc1 .LBB0_2417
.LBB0_2410:
	s_cmp_eq_u32 s36, 0
	s_cselect_b64 s[38:39], -1, 0
	s_and_b64 s[38:39], s[34:35], s[38:39]
	v_cndmask_b32_e64 v2, 0, 1, s[38:39]
	s_nop 0
	v_readfirstlane_b32 s38, v2
	s_and_b32 s38, s38, 1
	ds_read_b128 v[26:29], v224
	ds_read_b128 v[30:33], v224 offset:1024
	ds_read_b128 v[18:21], v224 offset:2048
	ds_read_b128 v[22:25], v224 offset:3072
	ds_read_b128 v[10:13], v225
	ds_read_b128 v[14:17], v225 offset:1024
	ds_read_b128 v[2:5], v225 offset:2048
	ds_read_b128 v[6:9], v225 offset:3072
	s_add_u32 s98, s30, s36
	s_addc_u32 s99, s31, s37
	s_add_i32 m0, s53, 0xc000
	ds_read_b128 v[58:61], v226
	ds_read_b128 v[62:65], v226 offset:1024
	ds_read_b128 v[50:53], v226 offset:2048
	ds_read_b128 v[54:57], v226 offset:3072
	ds_read_b128 v[42:45], v226 offset:4096
	ds_read_b128 v[46:49], v226 offset:5120
	ds_read_b128 v[34:37], v226 offset:6144
	ds_read_b128 v[38:41], v226 offset:7168
	global_load_lds_dwordx4 v204, s[98:99]
	s_add_i32 m0, s53, 0xe000
	s_cmp_lg_u32 s38, 0
	global_load_lds_dwordx4 v202, s[98:99]
	s_cselect_b64 s[42:43], -1, 0
	s_cmp_eq_u32 s38, 0
	s_cbranch_scc1 .LBB0_2415
	s_waitcnt vmcnt(24)
	s_cbranch_execnz .LBB0_2413

.LBB0_2413:
	s_add_u32 s38, s30, s36
	s_addc_u32 s39, s31, s37
	s_add_u32 s38, s38, 0x100
	s_addc_u32 s39, s39, 0
	s_add_u32 s77, s74, s36
	s_addc_u32 s78, s75, s37
	s_waitcnt lgkmcnt(0)
	s_cmpk_eq_i32 s36, 0x700
	s_cselect_b32 s41, s21, s39
	s_cselect_b32 s40, s72, s38
	s_cselect_b32 s39, s23, s78
	s_cselect_b32 s38, s73, s77
	s_barrier
	s_setprio 1
	s_waitcnt lgkmcnt(0)
	v_mfma_f32_16x16x128_f8f6f4 v[190:193], v[26:33], v[58:65], v[190:193]
	v_mfma_f32_16x16x128_f8f6f4 v[186:189], v[18:25], v[58:65], v[186:189]
	v_mfma_f32_16x16x128_f8f6f4 v[178:181], v[26:33], v[50:57], v[178:181]
	v_mfma_f32_16x16x128_f8f6f4 v[170:173], v[18:25], v[50:57], v[170:173]
	v_mfma_f32_16x16x128_f8f6f4 v[162:165], v[26:33], v[42:49], v[162:165]
	v_mfma_f32_16x16x128_f8f6f4 v[154:157], v[18:25], v[42:49], v[154:157]
	v_mfma_f32_16x16x128_f8f6f4 v[146:149], v[26:33], v[34:41], v[146:149]
	v_mfma_f32_16x16x128_f8f6f4 v[138:141], v[18:25], v[34:41], v[138:141]
	s_setprio 0
	s_setprio 1
	v_mfma_f32_16x16x128_f8f6f4 v[182:185], v[10:17], v[58:65], v[182:185]
	v_mfma_f32_16x16x128_f8f6f4 v[174:177], v[2:9], v[58:65], v[174:177]
	v_mfma_f32_16x16x128_f8f6f4 v[166:169], v[10:17], v[50:57], v[166:169]
	v_mfma_f32_16x16x128_f8f6f4 v[158:161], v[2:9], v[50:57], v[158:161]
	v_mfma_f32_16x16x128_f8f6f4 v[150:153], v[10:17], v[42:49], v[150:153]
	v_mfma_f32_16x16x128_f8f6f4 v[142:145], v[2:9], v[42:49], v[142:145]
	v_mfma_f32_16x16x128_f8f6f4 v[134:137], v[10:17], v[34:41], v[134:137]
	v_mfma_f32_16x16x128_f8f6f4 v[130:133], v[2:9], v[34:41], v[130:133]
	s_setprio 0
	s_barrier
	s_mov_b32 m0, s29
	s_add_u32 s78, s38, 0x40000
	ds_read_b128 v[58:61], v226 offset:16384
	ds_read_b128 v[62:65], v226 offset:17408
	ds_read_b128 v[50:53], v226 offset:18432
	ds_read_b128 v[54:57], v226 offset:19456
	ds_read_b128 v[42:45], v226 offset:20480
	ds_read_b128 v[46:49], v226 offset:21504
	ds_read_b128 v[34:37], v226 offset:22528
	ds_read_b128 v[38:41], v226 offset:23552
	global_load_lds_dwordx4 v196, s[38:39]
	s_mov_b32 m0, s50
	s_addc_u32 s79, s39, 0
	global_load_lds_dwordx4 v200, s[38:39]
	s_mov_b32 m0, s51
	s_nop 0
	global_load_lds_dwordx4 v196, s[78:79]
	s_mov_b32 m0, s52
	s_andn2_b64 vcc, exec, s[42:43]
	global_load_lds_dwordx4 v200, s[78:79]
	s_mov_b32 m0, s53
	s_nop 0
	global_load_lds_dwordx4 v194, s[40:41]
	s_mov_b32 m0, s54
	s_nop 0
	global_load_lds_dwordx4 v198, s[40:41]
	s_cbranch_vccnz .LBB0_2416
	s_waitcnt vmcnt(24)
	s_cbranch_execnz .LBB0_2409
	s_branch .LBB0_2408

.LBB0_2741:
	s_waitcnt lgkmcnt(0)
	s_barrier
	s_setprio 1
	s_waitcnt lgkmcnt(0)
	v_mfma_f32_16x16x32_bf16 v[62:65], v[146:149], v[186:189], v[62:65]
	v_mfma_f32_16x16x32_bf16 v[58:61], v[154:157], v[186:189], v[58:61]
	v_mfma_f32_16x16x32_bf16 v[54:57], v[146:149], v[178:181], v[54:57]
	v_mfma_f32_16x16x32_bf16 v[46:49], v[154:157], v[178:181], v[46:49]
	v_mfma_f32_16x16x32_bf16 v[38:41], v[146:149], v[170:173], v[38:41]
	v_mfma_f32_16x16x32_bf16 v[30:33], v[154:157], v[170:173], v[30:33]
	v_mfma_f32_16x16x32_bf16 v[22:25], v[146:149], v[162:165], v[22:25]
	v_mfma_f32_16x16x32_bf16 v[14:17], v[154:157], v[162:165], v[14:17]
	v_mfma_f32_16x16x32_bf16 v[62:65], v[150:153], v[190:193], v[62:65]
	v_mfma_f32_16x16x32_bf16 v[58:61], v[158:161], v[190:193], v[58:61]
	v_mfma_f32_16x16x32_bf16 v[54:57], v[150:153], v[182:185], v[54:57]
	v_mfma_f32_16x16x32_bf16 v[46:49], v[158:161], v[182:185], v[46:49]
	v_mfma_f32_16x16x32_bf16 v[38:41], v[150:153], v[174:177], v[38:41]
	v_mfma_f32_16x16x32_bf16 v[30:33], v[158:161], v[174:177], v[30:33]
	v_mfma_f32_16x16x32_bf16 v[22:25], v[150:153], v[166:169], v[22:25]
	v_mfma_f32_16x16x32_bf16 v[14:17], v[158:161], v[166:169], v[14:17]
	s_setprio 0
	s_setprio 1
	v_mfma_f32_16x16x32_bf16 v[50:53], v[130:133], v[186:189], v[50:53]
	v_mfma_f32_16x16x32_bf16 v[42:45], v[138:141], v[186:189], v[42:45]
	v_mfma_f32_16x16x32_bf16 v[34:37], v[130:133], v[178:181], v[34:37]
	v_mfma_f32_16x16x32_bf16 v[26:29], v[138:141], v[178:181], v[26:29]
	v_mfma_f32_16x16x32_bf16 v[18:21], v[130:133], v[170:173], v[18:21]
	v_mfma_f32_16x16x32_bf16 v[10:13], v[138:141], v[170:173], v[10:13]
	v_mfma_f32_16x16x32_bf16 v[6:9], v[130:133], v[162:165], v[6:9]
	v_mfma_f32_16x16x32_bf16 v[2:5], v[138:141], v[162:165], v[2:5]
	v_mfma_f32_16x16x32_bf16 v[50:53], v[134:137], v[190:193], v[50:53]
	v_mfma_f32_16x16x32_bf16 v[42:45], v[142:145], v[190:193], v[42:45]
	v_mfma_f32_16x16x32_bf16 v[34:37], v[134:137], v[182:185], v[34:37]
	v_mfma_f32_16x16x32_bf16 v[26:29], v[142:145], v[182:185], v[26:29]
	v_mfma_f32_16x16x32_bf16 v[18:21], v[134:137], v[174:177], v[18:21]
	v_mfma_f32_16x16x32_bf16 v[10:13], v[142:145], v[174:177], v[10:13]
	v_mfma_f32_16x16x32_bf16 v[6:9], v[134:137], v[166:169], v[6:9]
	v_mfma_f32_16x16x32_bf16 v[2:5], v[142:145], v[166:169], v[2:5]
	s_setprio 0
	s_barrier
	v_add_u32_e32 v142, s48, v222
	v_add_u32_e32 v158, s53, v222
	ds_read_b128 v[130:133], v142
	ds_read_b128 v[134:137], v142 offset:1024
	ds_read_b128 v[138:141], v142 offset:2048
	ds_read_b128 v[142:145], v142 offset:3072
	ds_read_b128 v[146:149], v158
	ds_read_b128 v[150:153], v158 offset:1024
	ds_read_b128 v[154:157], v158 offset:2048
	ds_read_b128 v[158:161], v158 offset:3072
	s_add_u32 s100, s30, 0x160000
	s_addc_u32 s101, s31, 0
	s_mov_b32 m0, s46
	ds_read_b128 v[162:165], v226 offset:32768
	ds_read_b128 v[166:169], v226 offset:33792
	ds_read_b128 v[170:173], v226 offset:34816
	ds_read_b128 v[174:177], v226 offset:35840
	ds_read_b128 v[178:181], v226 offset:36864
	ds_read_b128 v[182:185], v226 offset:37888
	ds_read_b128 v[186:189], v226 offset:38912
	ds_read_b128 v[190:193], v226 offset:39936
	global_load_lds_dwordx4 v194, s[100:101]
	s_mov_b32 m0, s47
	s_nop 0
	global_load_lds_dwordx4 v198, s[100:101]
	s_waitcnt vmcnt(8)
	s_waitcnt lgkmcnt(0)
	s_barrier
	s_setprio 1
	s_waitcnt lgkmcnt(0)
	v_mfma_f32_16x16x32_bf16 v[126:129], v[130:133], v[162:165], v[126:129]
	v_mfma_f32_16x16x32_bf16 v[122:125], v[138:141], v[162:165], v[122:125]
	v_mfma_f32_16x16x32_bf16 v[118:121], v[130:133], v[170:173], v[118:121]
	v_mfma_f32_16x16x32_bf16 v[110:113], v[138:141], v[170:173], v[110:113]
	v_mfma_f32_16x16x32_bf16 v[102:105], v[130:133], v[178:181], v[102:105]
	v_mfma_f32_16x16x32_bf16 v[94:97], v[138:141], v[178:181], v[94:97]
	v_mfma_f32_16x16x32_bf16 v[86:89], v[130:133], v[186:189], v[86:89]
	v_mfma_f32_16x16x32_bf16 v[78:81], v[138:141], v[186:189], v[78:81]
	v_mfma_f32_16x16x32_bf16 v[126:129], v[134:137], v[166:169], v[126:129]
	v_mfma_f32_16x16x32_bf16 v[122:125], v[142:145], v[166:169], v[122:125]
	v_mfma_f32_16x16x32_bf16 v[118:121], v[134:137], v[174:177], v[118:121]
	v_mfma_f32_16x16x32_bf16 v[110:113], v[142:145], v[174:177], v[110:113]
	v_mfma_f32_16x16x32_bf16 v[102:105], v[134:137], v[182:185], v[102:105]
	v_mfma_f32_16x16x32_bf16 v[94:97], v[142:145], v[182:185], v[94:97]
	v_mfma_f32_16x16x32_bf16 v[86:89], v[134:137], v[190:193], v[86:89]
	v_mfma_f32_16x16x32_bf16 v[78:81], v[142:145], v[190:193], v[78:81]
	s_setprio 0
	s_setprio 1
	v_mfma_f32_16x16x32_bf16 v[114:117], v[146:149], v[162:165], v[114:117]
	v_mfma_f32_16x16x32_bf16 v[106:109], v[154:157], v[162:165], v[106:109]
	v_mfma_f32_16x16x32_bf16 v[98:101], v[146:149], v[170:173], v[98:101]
	v_mfma_f32_16x16x32_bf16 v[90:93], v[154:157], v[170:173], v[90:93]
	v_mfma_f32_16x16x32_bf16 v[82:85], v[146:149], v[178:181], v[82:85]
	v_mfma_f32_16x16x32_bf16 v[74:77], v[154:157], v[178:181], v[74:77]
	v_mfma_f32_16x16x32_bf16 v[70:73], v[146:149], v[186:189], v[70:73]
	v_mfma_f32_16x16x32_bf16 v[66:69], v[154:157], v[186:189], v[66:69]
	v_mfma_f32_16x16x32_bf16 v[114:117], v[150:153], v[166:169], v[114:117]
	v_mfma_f32_16x16x32_bf16 v[106:109], v[158:161], v[166:169], v[106:109]
	v_mfma_f32_16x16x32_bf16 v[98:101], v[150:153], v[174:177], v[98:101]
	v_mfma_f32_16x16x32_bf16 v[90:93], v[158:161], v[174:177], v[90:93]
	v_mfma_f32_16x16x32_bf16 v[82:85], v[150:153], v[182:185], v[82:85]
	v_mfma_f32_16x16x32_bf16 v[74:77], v[158:161], v[182:185], v[74:77]
	v_mfma_f32_16x16x32_bf16 v[70:73], v[150:153], v[190:193], v[70:73]
	v_mfma_f32_16x16x32_bf16 v[66:69], v[158:161], v[190:193], v[66:69]
	s_setprio 0
	s_barrier
	s_mov_b32 m0, s49
	ds_read_b128 v[162:165], v226 offset:49152
	ds_read_b128 v[166:169], v226 offset:50176
	ds_read_b128 v[170:173], v226 offset:51200
	ds_read_b128 v[174:177], v226 offset:52224
	ds_read_b128 v[178:181], v226 offset:53248
	ds_read_b128 v[182:185], v226 offset:54272
	ds_read_b128 v[186:189], v226 offset:55296
	ds_read_b128 v[190:193], v226 offset:56320
	s_add_u32 s98, s28, 0x80
	s_addc_u32 s99, s29, 0
	global_load_lds_dwordx4 v196, s[98:99]
	s_mov_b32 m0, s50
	s_nop 0
	global_load_lds_dwordx4 v200, s[98:99]
	s_mov_b32 m0, s54
	s_nop 0
	s_add_u32 s100, s70, 0x80
	s_addc_u32 s101, s71, 0
	global_load_lds_dwordx4 v196, s[100:101]
	s_mov_b32 m0, s55
	s_nop 0
	global_load_lds_dwordx4 v200, s[100:101]
	s_mov_b32 m0, s51
	s_nop 0
	s_add_u32 s98, s30, 0x80
	s_addc_u32 s99, s31, 0
	global_load_lds_dwordx4 v194, s[98:99]
	s_mov_b32 m0, s52
	s_nop 0
	global_load_lds_dwordx4 v198, s[98:99]
	s_waitcnt vmcnt(8)
	s_waitcnt lgkmcnt(0)
	s_barrier
	s_setprio 1
	s_waitcnt lgkmcnt(0)
	v_mfma_f32_16x16x32_bf16 v[62:65], v[130:133], v[162:165], v[62:65]
	v_mfma_f32_16x16x32_bf16 v[58:61], v[138:141], v[162:165], v[58:61]
	v_mfma_f32_16x16x32_bf16 v[54:57], v[130:133], v[170:173], v[54:57]
	v_mfma_f32_16x16x32_bf16 v[46:49], v[138:141], v[170:173], v[46:49]
	v_mfma_f32_16x16x32_bf16 v[38:41], v[130:133], v[178:181], v[38:41]
	v_mfma_f32_16x16x32_bf16 v[30:33], v[138:141], v[178:181], v[30:33]
	v_mfma_f32_16x16x32_bf16 v[22:25], v[130:133], v[186:189], v[22:25]
	v_mfma_f32_16x16x32_bf16 v[14:17], v[138:141], v[186:189], v[14:17]
	v_mfma_f32_16x16x32_bf16 v[62:65], v[134:137], v[166:169], v[62:65]
	v_mfma_f32_16x16x32_bf16 v[58:61], v[142:145], v[166:169], v[58:61]
	v_mfma_f32_16x16x32_bf16 v[54:57], v[134:137], v[174:177], v[54:57]
	v_mfma_f32_16x16x32_bf16 v[46:49], v[142:145], v[174:177], v[46:49]
	v_mfma_f32_16x16x32_bf16 v[38:41], v[134:137], v[182:185], v[38:41]
	v_mfma_f32_16x16x32_bf16 v[30:33], v[142:145], v[182:185], v[30:33]
	v_mfma_f32_16x16x32_bf16 v[22:25], v[134:137], v[190:193], v[22:25]
	v_mfma_f32_16x16x32_bf16 v[14:17], v[142:145], v[190:193], v[14:17]
	s_setprio 0
	s_setprio 1
	v_mfma_f32_16x16x32_bf16 v[50:53], v[146:149], v[162:165], v[50:53]
	v_mfma_f32_16x16x32_bf16 v[42:45], v[154:157], v[162:165], v[42:45]
	v_mfma_f32_16x16x32_bf16 v[34:37], v[146:149], v[170:173], v[34:37]
	v_mfma_f32_16x16x32_bf16 v[26:29], v[154:157], v[170:173], v[26:29]
	v_mfma_f32_16x16x32_bf16 v[18:21], v[146:149], v[178:181], v[18:21]
	v_mfma_f32_16x16x32_bf16 v[10:13], v[154:157], v[178:181], v[10:13]
	v_mfma_f32_16x16x32_bf16 v[6:9], v[146:149], v[186:189], v[6:9]
	v_mfma_f32_16x16x32_bf16 v[2:5], v[154:157], v[186:189], v[2:5]
	v_mfma_f32_16x16x32_bf16 v[50:53], v[150:153], v[166:169], v[50:53]
	v_mfma_f32_16x16x32_bf16 v[42:45], v[158:161], v[166:169], v[42:45]
	v_mfma_f32_16x16x32_bf16 v[34:37], v[150:153], v[174:177], v[34:37]
	v_mfma_f32_16x16x32_bf16 v[26:29], v[158:161], v[174:177], v[26:29]
	v_mfma_f32_16x16x32_bf16 v[18:21], v[150:153], v[182:185], v[18:21]
	v_mfma_f32_16x16x32_bf16 v[10:13], v[158:161], v[182:185], v[10:13]
	v_mfma_f32_16x16x32_bf16 v[6:9], v[150:153], v[190:193], v[6:9]
	v_mfma_f32_16x16x32_bf16 v[2:5], v[158:161], v[190:193], v[2:5]
	s_setprio 0
	s_barrier
	s_add_i32 s69, s69, 2
	s_add_u32 s26, s26, 0x100
	s_addc_u32 s27, s27, 0
	s_cmpk_gt_u32 s69, 0x55
	s_cbranch_scc1 .LBB0_2749
.LBB0_2742:
	s_cmp_eq_u32 s26, 0
	s_cselect_b64 s[28:29], -1, 0
	s_and_b64 s[28:29], s[24:25], s[28:29]
	v_cndmask_b32_e64 v130, 0, 1, s[28:29]
	s_nop 0
	v_readfirstlane_b32 s28, v130
	s_and_b32 s28, s28, 1
	ds_read_b128 v[146:149], v224
	ds_read_b128 v[150:153], v224 offset:1024
	ds_read_b128 v[154:157], v224 offset:2048
	ds_read_b128 v[158:161], v224 offset:3072
	ds_read_b128 v[130:133], v225
	ds_read_b128 v[134:137], v225 offset:1024
	ds_read_b128 v[138:141], v225 offset:2048
	ds_read_b128 v[142:145], v225 offset:3072
	s_add_u32 s98, s22, s26
	s_addc_u32 s99, s23, s27
	s_add_i32 m0, s44, 0xc000
	ds_read_b128 v[186:189], v226
	ds_read_b128 v[190:193], v226 offset:1024
	ds_read_b128 v[178:181], v226 offset:2048
	ds_read_b128 v[182:185], v226 offset:3072
	ds_read_b128 v[170:173], v226 offset:4096
	ds_read_b128 v[174:177], v226 offset:5120
	ds_read_b128 v[162:165], v226 offset:6144
	ds_read_b128 v[166:169], v226 offset:7168
	global_load_lds_dwordx4 v204, s[98:99]
	s_add_i32 m0, s44, 0xe000
	s_cmp_lg_u32 s28, 0
	global_load_lds_dwordx4 v202, s[98:99]
	s_cselect_b64 s[34:35], -1, 0
	s_cmp_eq_u32 s28, 0
	s_cbranch_scc1 .LBB0_2747
	s_waitcnt vmcnt(24)
	s_cbranch_execnz .LBB0_2745

.LBB0_2745:
	s_add_u32 s28, s22, s26
	s_addc_u32 s29, s23, s27
	s_add_u32 s28, s28, 0x100
	s_addc_u32 s29, s29, 0
	s_add_u32 s70, s67, s26
	s_addc_u32 s71, s68, s27
	s_waitcnt lgkmcnt(0)
	s_cmpk_eq_i32 s26, 0x2b00
	s_cselect_b32 s31, s1, s29
	s_cselect_b32 s30, s0, s28
	s_cselect_b32 s29, s21, s71
	s_cselect_b32 s28, s20, s70
	s_barrier
	s_setprio 1
	s_waitcnt lgkmcnt(0)
	v_mfma_f32_16x16x32_bf16 v[126:129], v[146:149], v[186:189], v[126:129]
	v_mfma_f32_16x16x32_bf16 v[122:125], v[154:157], v[186:189], v[122:125]
	v_mfma_f32_16x16x32_bf16 v[118:121], v[146:149], v[178:181], v[118:121]
	v_mfma_f32_16x16x32_bf16 v[110:113], v[154:157], v[178:181], v[110:113]
	v_mfma_f32_16x16x32_bf16 v[102:105], v[146:149], v[170:173], v[102:105]
	v_mfma_f32_16x16x32_bf16 v[94:97], v[154:157], v[170:173], v[94:97]
	v_mfma_f32_16x16x32_bf16 v[86:89], v[146:149], v[162:165], v[86:89]
	v_mfma_f32_16x16x32_bf16 v[78:81], v[154:157], v[162:165], v[78:81]
	v_mfma_f32_16x16x32_bf16 v[126:129], v[150:153], v[190:193], v[126:129]
	v_mfma_f32_16x16x32_bf16 v[122:125], v[158:161], v[190:193], v[122:125]
	v_mfma_f32_16x16x32_bf16 v[118:121], v[150:153], v[182:185], v[118:121]
	v_mfma_f32_16x16x32_bf16 v[110:113], v[158:161], v[182:185], v[110:113]
	v_mfma_f32_16x16x32_bf16 v[102:105], v[150:153], v[174:177], v[102:105]
	v_mfma_f32_16x16x32_bf16 v[94:97], v[158:161], v[174:177], v[94:97]
	v_mfma_f32_16x16x32_bf16 v[86:89], v[150:153], v[166:169], v[86:89]
	v_mfma_f32_16x16x32_bf16 v[78:81], v[158:161], v[166:169], v[78:81]
	s_setprio 0
	s_setprio 1
	v_mfma_f32_16x16x32_bf16 v[114:117], v[130:133], v[186:189], v[114:117]
	v_mfma_f32_16x16x32_bf16 v[106:109], v[138:141], v[186:189], v[106:109]
	v_mfma_f32_16x16x32_bf16 v[98:101], v[130:133], v[178:181], v[98:101]
	v_mfma_f32_16x16x32_bf16 v[90:93], v[138:141], v[178:181], v[90:93]
	v_mfma_f32_16x16x32_bf16 v[82:85], v[130:133], v[170:173], v[82:85]
	v_mfma_f32_16x16x32_bf16 v[74:77], v[138:141], v[170:173], v[74:77]
	v_mfma_f32_16x16x32_bf16 v[70:73], v[130:133], v[162:165], v[70:73]
	v_mfma_f32_16x16x32_bf16 v[66:69], v[138:141], v[162:165], v[66:69]
	v_mfma_f32_16x16x32_bf16 v[114:117], v[134:137], v[190:193], v[114:117]
	v_mfma_f32_16x16x32_bf16 v[106:109], v[142:145], v[190:193], v[106:109]
	v_mfma_f32_16x16x32_bf16 v[98:101], v[134:137], v[182:185], v[98:101]
	v_mfma_f32_16x16x32_bf16 v[90:93], v[142:145], v[182:185], v[90:93]
	v_mfma_f32_16x16x32_bf16 v[82:85], v[134:137], v[174:177], v[82:85]
	v_mfma_f32_16x16x32_bf16 v[74:77], v[142:145], v[174:177], v[74:77]
	v_mfma_f32_16x16x32_bf16 v[70:73], v[134:137], v[166:169], v[70:73]
	v_mfma_f32_16x16x32_bf16 v[66:69], v[142:145], v[166:169], v[66:69]
	s_setprio 0
	s_barrier
	s_mov_b32 m0, s40
	s_add_u32 s70, s28, 0x160000
	ds_read_b128 v[186:189], v226 offset:16384
	ds_read_b128 v[190:193], v226 offset:17408
	ds_read_b128 v[178:181], v226 offset:18432
	ds_read_b128 v[182:185], v226 offset:19456
	ds_read_b128 v[170:173], v226 offset:20480
	ds_read_b128 v[174:177], v226 offset:21504
	ds_read_b128 v[162:165], v226 offset:22528
	ds_read_b128 v[166:169], v226 offset:23552
	global_load_lds_dwordx4 v196, s[28:29]
	s_mov_b32 m0, s41
	s_addc_u32 s71, s29, 0
	global_load_lds_dwordx4 v200, s[28:29]
	s_mov_b32 m0, s42
	s_nop 0
	global_load_lds_dwordx4 v196, s[70:71]
	s_mov_b32 m0, s43
	s_andn2_b64 vcc, exec, s[34:35]
	global_load_lds_dwordx4 v200, s[70:71]
	s_mov_b32 m0, s44
	s_nop 0
	global_load_lds_dwordx4 v194, s[30:31]
	s_mov_b32 m0, s45
	s_nop 0
	global_load_lds_dwordx4 v198, s[30:31]
	s_cbranch_vccnz .LBB0_2748
	s_waitcnt vmcnt(24)
	s_cbranch_execnz .LBB0_2741
	s_branch .LBB0_2740
